# v6b + MMAX extra-row MFMAs accumulate in place (no copy-back tail)
# speedup vs baseline: 1.0310x; 1.0015x over previous
; DI void phase_prologue(const Frame& F0, const Args& a) {
;     ...
;         const int gw = F.vcu * NWAVES + F.wave, NGW = F.G * NWAVES;
;         constexpr int I_IN = 32 * (GIN / 32), I_SQ = 32 * 64, I_GU = 32 * (2 * DFF / 32), I_DN = (DFF / 64) * 64;
;         constexpr int NITEMS = 2 * I_IN + 2 * I_SQ + 2 * I_SQ + DEPTH * I_GU + DEPTH * I_DN;
;         for (int it = gw; it < NITEMS; it += NGW) {
.LBB0_79:
	s_or_b64 exec, exec, s[8:9]
	s_lshl_b32 s0, s60, 3
	s_add_i32 s6, s0, s44
	s_cmp_gt_i32 s6, 0x1583f
	s_cbranch_scc1 .LBB0_11
	s_mov_b32 s90, s6
	s_mov_b32 s92, 0
	s_mov_b32 s91, 0x15840
	v_readlane_b32 s93, v252, 53
	s_cmp_eq_u32 s3, 0x100
	s_cbranch_scc0 .Lconv_entry
	s_mov_b32 s92, 1
	s_mov_b32 s91, 0x8cb4

; DI void phase_prologue(const Frame& F0, const Args& a) {
;     ...
;         for (int it = gw; it < NITEMS; it += NGW) {
;             int r = it;
;             if (r < 2 * I_IN) { const int j = r / I_IN; r %= I_IN; const int nblk = GIN / 32, kb = r / nblk, nb = r % nblk;
;                 transpose_item(a.gla_w_in + (size_t)j * DM * GIN, DM, GIN, (bf16*)(ws + WS_WIN) + (size_t)j * GIN_PAD * DM, 64 * kb, 32 * nb, 32 * nb, scr, F.lane); continue; }
;             r -= 2 * I_IN;
;             if (r < 2 * I_SQ) { const int j = r / I_SQ; r %= I_SQ; const int kb = r / 64, nb = r % 64;
;                 transpose_item(a.gla_w_out + (size_t)j * DM * DM, DM, DM, (bf16*)(ws + WS_WGO) + (size_t)j * DM * DM, 64 * kb, 32 * nb, 32 * nb, scr, F.lane); continue; }
;             r -= 2 * I_SQ;
;             if (r < 2 * I_SQ) { const int j = r / I_SQ; r %= I_SQ; const int kb = r / 64, nb = r % 64;
;                 transpose_item(a.fnet_w_out + (size_t)j * DM * DM, DM, DM, (bf16*)(ws + WS_WFO) + (size_t)j * DM * DM, 64 * kb, 32 * nb, 32 * nb, scr, F.lane, 1); continue; }
;             r -= 2 * I_SQ;
;             if (r < DEPTH * I_GU) { const int j = r / I_GU; r %= I_GU; const int nblk = 2 * DFF / 32, kb = r / nblk, nb = r % nblk, n0 = 32 * nb;
;                 const int jj = n0 < DFF ? n0 : n0 - DFF; const int drow = (jj >> 7) * 256 + (n0 < DFF ? 0 : 128) + (jj & 127);
;                 transpose_item(a.ffn_w_gu + (size_t)j * DM * 2 * DFF, DM, 2 * DFF, (bf16*)(ws + WS_WGU) + (size_t)j * 2 * DFF * DM, 64 * kb, n0, drow, scr, F.lane); continue; }
;             r -= DEPTH * I_GU;
;             { const int j = r / I_DN; r %= I_DN; const int kb = r / 64, nb = r % 64;
;                 transpose_item(a.ffn_w_down + (size_t)j * DFF * DM, DFF, DM, (bf16*)(ws + WS_WDN) + (size_t)j * DM * DFF, 64 * kb, 32 * nb, 32 * nb, scr, F.lane); }
.LBB0_82:
	s_add_i32 s94, s90, s86
	s_cmp_eq_u32 s92, 0
	s_cbranch_scc1 .Lconv_map0
	s_cmp_eq_u32 s92, 1
	s_cbranch_scc1 .Lconv_map1
	s_cmp_eq_u32 s92, 2
	s_cbranch_scc1 .Lconv_map2
	s_mov_b32 s0, 0xf288
	s_cmp_lt_i32 s90, 0x39b8
	s_cselect_b32 s0, 0xc688, s0
	s_cmp_lt_i32 s90, 0x800
	s_cselect_b32 s0, 0x4840, s0
	s_add_i32 s6, s90, s0
	s_branch .Lconv_mapped
.Lconv_map2:
	s_mov_b32 s0, 0xc66c
	s_cmp_lt_i32 s90, 0x4fd4
	s_cselect_b32 s0, 0x586c, s0
	s_cmp_lt_i32 s90, 0x2820
	s_cselect_b32 s0, 0x2020, s0
	s_cmp_lt_i32 s90, 0x1820
	s_cselect_b32 s0, 0x1820, s0
	s_add_i32 s6, s90, s0
	s_branch .Lconv_mapped
.Lconv_map1:
	s_mov_b32 s0, 0x898c
	s_cmp_lt_i32 s90, 0x76b4
	s_cselect_b32 s0, 0x57d4, s0
	s_cmp_lt_i32 s90, 0x506c
	s_cselect_b32 s0, 0x3020, s0
	s_cmp_lt_i32 s90, 0x2020
	s_cselect_b32 s0, 0x1820, s0
	s_cmp_lt_i32 s90, 0x1820
	s_cselect_b32 s0, 0x0, s0
	s_add_i32 s6, s90, s0
	s_branch .Lconv_mapped
.Lconv_map0:
	s_mov_b32 s6, s90
	s_mov_b32 s95, s94

; DI void phase_prologue(const Frame& F0, const Args& a) {
;     ...
;         const int gw = F.vcu * NWAVES + F.wave, NGW = F.G * NWAVES;
;         constexpr int I_IN = 32 * (GIN / 32), I_SQ = 32 * 64, I_GU = 32 * (2 * DFF / 32), I_DN = (DFF / 64) * 64;
;         constexpr int NITEMS = 2 * I_IN + 2 * I_SQ + 2 * I_SQ + DEPTH * I_GU + DEPTH * I_DN;
;         for (int it = gw; it < NITEMS; it += NGW) {
; DI void phase_scan(const Frame& F0, const Args& a, int colmajor) {
;     ...
;     for (int it = F.vcu; it < 256; it += F.G) {
;         if ((it & 31) >= 16) continue;
.Lconv_scan_idle:
	s_cmp_eq_u32 s3, 0x100
	s_cbranch_scc0 .LBB0_821
	v_writelane_b32 v100, s11, 0
	v_writelane_b32 v100, s20, 1
	v_writelane_b32 v100, s21, 2
	v_writelane_b32 v100, s22, 3
	v_writelane_b32 v100, s26, 4
	v_writelane_b32 v100, s28, 5
	v_writelane_b32 v100, s29, 6
	v_writelane_b32 v100, s30, 7
	v_writelane_b32 v100, s31, 8
	v_writelane_b32 v100, s44, 9
	v_writelane_b32 v100, s45, 10
	v_writelane_b32 v100, s48, 11
	v_writelane_b32 v100, s49, 12
	v_writelane_b32 v100, s50, 13
	v_writelane_b32 v100, s51, 14
	v_writelane_b32 v100, s52, 15
	v_writelane_b32 v100, s53, 16
	v_writelane_b32 v100, s54, 17
	v_writelane_b32 v100, s55, 18
	v_writelane_b32 v100, s57, 19
	v_writelane_b32 v100, s58, 20
	v_writelane_b32 v100, s59, 21
	v_writelane_b32 v100, s64, 22
	v_writelane_b32 v100, s73, 23
	v_writelane_b32 v100, s80, 24
	v_writelane_b32 v100, s81, 25
	v_writelane_b32 v100, s83, 26
	v_writelane_b32 v100, s86, 27
	v_writelane_b32 v100, s87, 28
	v_mov_b32_e32 v101, v1
	v_mov_b32_e32 v102, v3
	v_readlane_b32 s0, v255, 17
	v_readlane_b32 s1, v252, 48
	v_readlane_b32 s44, v252, 49
	v_readlane_b32 s86, v252, 46
	v_readlane_b32 s87, v252, 47
	s_movk_i32 s34, 0xfe00
	s_mov_b32 s65, 0
	s_movk_i32 s70, 0x101
	s_movk_i32 s73, 0x6080
	v_mov_b32_e32 v55, 0
	v_mov_b32_e32 v78, v222
	s_lshr_b32 s4, s1, 5
	s_lshl_b32 s4, s4, 4
	s_and_b32 s5, s1, 15
	s_or_b32 s4, s4, s5
	s_lshl_b32 s4, s4, 3
	s_add_i32 s90, s4, s44
	s_movk_i32 s93, 0x400
	s_mov_b32 s4, 0x65d4
	s_mov_b32 s5, 0x65b8
	s_cmp_eq_u32 s0, 0
	s_cselect_b32 s92, 2, 3
	s_cselect_b32 s91, s4, s5
	s_mov_b32 s6, s90
	s_cmp_lt_i32 s90, s91
	s_cbranch_scc1 .Lconv_entry

; #define PG8_STAGE(bufoff, gbase, voff) do { _Pragma("unroll") for (int _i = 0; _i < 2; ++_i) glds16_s((voff)[_i], (const void*)(gbase), ldsbase + (unsigned)((bufoff) + _i * 8192) + ldsw); } while (0)
; #define PG8_LDA(dst, b, h) do { _Pragma("unroll") for (int m = 0; m < 4; ++m) _Pragma("unroll") for (int k = 0; k < 2; ++k) dst[m][k] = *(const PG8_LAS bf16x8*)(lds + PG8_SA(b, h) + aoff + m * 2048 + k * 1024); } while (0)
; #define PG8_MMA(ai, bj, At, Bt) do { __builtin_amdgcn_s_setprio(1); _Pragma("unroll") for (int m = 0; m < 4; ++m) _Pragma("unroll") for (int n = 0; n < 2; ++n) _Pragma("unroll") for (int k = 0; k < 2; ++k) \
;         acc[ai][bj][m][n] = __builtin_amdgcn_mfma_f32_16x16x32_bf16(Bt[n][k], At[m][k], acc[ai][bj][m][n], 0, 0, 0); __builtin_amdgcn_s_setprio(0); } while (0)
; #define PG8_WAIT_V(n) asm volatile("s_waitcnt vmcnt(" #n ")" ::: "memory")
; #define PG8_WAIT_L(n) asm volatile("s_waitcnt lgkmcnt(" #n ")" ::: "memory")
; #define PG8_BAR __builtin_amdgcn_s_barrier()
; #define PG8_SCHED __builtin_amdgcn_sched_barrier(0)
; template <class Epi, class Sched, bool HM = false>
; __device__ __forceinline__ void gemm_phase(PG8_LAS unsigned char* lds, const Gemm g, const Sched& S, const Epi& E) {
;     ...
;             if (!HM) PG8_LDA(At, 1, 1); PG8_STAGE(PG8_SB(1, 0), b3, voffB); PG8_STAGE(PG8_SB(1, 1), b3 + hstepB, voffB); PG8_STAGE(PG8_SA(1, 0), a3, voffA);
;             PG8_WAIT_V(8); PG8_WAIT_L(0); PG8_BAR; if (!HM) { PG8_MMA(1, 0, At, B0); PG8_MMA(1, 1, At, B1); } PG8_BAR; PG8_SCHED;
;         }
.LBB0_254:
.LBB0_255:
	s_barrier
	ds_read_b128 v[182:185], v235 offset:49152
	ds_read_b128 v[186:189], v235 offset:50176
	ds_read_b128 v[190:193], v235 offset:51200
	ds_read_b128 v[194:197], v235 offset:52224
	ds_read_b128 v[198:201], v235 offset:53248
	ds_read_b128 v[202:205], v235 offset:54272
	ds_read_b128 v[206:209], v235 offset:55296
	ds_read_b128 v[210:213], v235 offset:56320
	s_mov_b32 s8, m0
	s_mov_b32 m0, s36
	s_nop 0
	global_load_lds_dwordx4 v226, s[6:7]
	s_mov_b32 m0, s8
	s_nop 0
	s_mov_b32 s8, m0
	s_mov_b32 m0, s37
	s_nop 0
	global_load_lds_dwordx4 v228, s[6:7]
	s_mov_b32 m0, s8
	s_add_u32 s6, s6, 0x20000
	s_addc_u32 s7, s7, 0
	s_mov_b32 s8, m0
	s_mov_b32 m0, s57
	s_nop 0
	global_load_lds_dwordx4 v226, s[6:7]
	s_mov_b32 m0, s8
	s_nop 0
	s_mov_b32 s8, m0
	s_mov_b32 m0, s58
	s_nop 0
	global_load_lds_dwordx4 v228, s[6:7]
	s_mov_b32 m0, s8
	s_mov_b32 s6, m0
	s_mov_b32 m0, s51
	s_nop 0
	global_load_lds_dwordx4 v225, s[4:5]
	s_mov_b32 m0, s6
	s_nop 0
	s_mov_b32 s6, m0
	s_mov_b32 m0, s52
	s_nop 0
	global_load_lds_dwordx4 v227, s[4:5]
	s_mov_b32 m0, s6
	s_waitcnt vmcnt(8)
	s_waitcnt lgkmcnt(0)
	s_barrier
	s_setprio 1
	s_waitcnt lgkmcnt(7)
	v_mfma_f32_16x16x32_bf16 v[82:85], v[166:169], v[182:185], v[82:85]
	v_mfma_f32_16x16x32_bf16 v[78:81], v[174:177], v[182:185], v[78:81]
	s_waitcnt lgkmcnt(5)
	v_mfma_f32_16x16x32_bf16 v[74:77], v[166:169], v[190:193], v[74:77]
	v_mfma_f32_16x16x32_bf16 v[66:69], v[174:177], v[190:193], v[66:69]
	s_waitcnt lgkmcnt(3)
	v_mfma_f32_16x16x32_bf16 v[58:61], v[166:169], v[198:201], v[58:61]
	v_mfma_f32_16x16x32_bf16 v[50:53], v[174:177], v[198:201], v[50:53]
	s_waitcnt lgkmcnt(1)
	v_mfma_f32_16x16x32_bf16 v[42:45], v[166:169], v[206:209], v[42:45]
	v_mfma_f32_16x16x32_bf16 v[34:37], v[174:177], v[206:209], v[34:37]
	v_mfma_f32_16x16x32_bf16 v[82:85], v[170:173], v[186:189], v[82:85]
	v_mfma_f32_16x16x32_bf16 v[78:81], v[178:181], v[186:189], v[78:81]
	v_mfma_f32_16x16x32_bf16 v[74:77], v[170:173], v[194:197], v[74:77]
	v_mfma_f32_16x16x32_bf16 v[66:69], v[178:181], v[194:197], v[66:69]
	v_mfma_f32_16x16x32_bf16 v[58:61], v[170:173], v[202:205], v[58:61]
	v_mfma_f32_16x16x32_bf16 v[50:53], v[178:181], v[202:205], v[50:53]
	s_waitcnt lgkmcnt(0)
	v_mfma_f32_16x16x32_bf16 v[42:45], v[170:173], v[210:213], v[42:45]
	v_mfma_f32_16x16x32_bf16 v[34:37], v[178:181], v[210:213], v[34:37]
	s_setprio 0
	s_setprio 1
	v_mfma_f32_16x16x32_bf16 v[70:73], v[150:153], v[182:185], v[70:73]
	v_mfma_f32_16x16x32_bf16 v[62:65], v[158:161], v[182:185], v[62:65]
	v_mfma_f32_16x16x32_bf16 v[54:57], v[150:153], v[190:193], v[54:57]
	v_mfma_f32_16x16x32_bf16 v[46:49], v[158:161], v[190:193], v[46:49]
	v_mfma_f32_16x16x32_bf16 v[38:41], v[150:153], v[198:201], v[38:41]
	v_mfma_f32_16x16x32_bf16 v[30:33], v[158:161], v[198:201], v[30:33]
	v_mfma_f32_16x16x32_bf16 v[26:29], v[150:153], v[206:209], v[26:29]
	v_mfma_f32_16x16x32_bf16 v[22:25], v[158:161], v[206:209], v[22:25]
	v_mfma_f32_16x16x32_bf16 v[70:73], v[154:157], v[186:189], v[70:73]
	v_mfma_f32_16x16x32_bf16 v[62:65], v[162:165], v[186:189], v[62:65]
	v_mfma_f32_16x16x32_bf16 v[54:57], v[154:157], v[194:197], v[54:57]
	v_mfma_f32_16x16x32_bf16 v[46:49], v[162:165], v[194:197], v[46:49]
	v_mfma_f32_16x16x32_bf16 v[38:41], v[154:157], v[202:205], v[38:41]
	v_mfma_f32_16x16x32_bf16 v[30:33], v[162:165], v[202:205], v[30:33]
	v_mfma_f32_16x16x32_bf16 v[26:29], v[154:157], v[210:213], v[26:29]
	v_mfma_f32_16x16x32_bf16 v[22:25], v[162:165], v[210:213], v[22:25]
	s_setprio 0
	s_barrier
	s_add_i32 s23, s23, 2
	s_addk_i32 s22, 0x1000
	s_add_u32 s95, s95, 0x100
	s_addc_u32 s38, s38, 0
	s_add_u32 s27, s27, 0x100
	s_addc_u32 s39, s39, 0
	s_cmp_gt_u32 s23, 5
	s_cbranch_scc1 .LBB0_271

; #define PG8_STAGE(bufoff, gbase, voff) do { _Pragma("unroll") for (int _i = 0; _i < 2; ++_i) glds16_s((voff)[_i], (const void*)(gbase), ldsbase + (unsigned)((bufoff) + _i * 8192) + ldsw); } while (0)
; #define PG8_STAGEX(pb, gbase) glds16_s(voffX, (const void*)(gbase), ldsbase + (unsigned)(XOFF + (pb) * 4096) + ldsx)
; #define PG8_LDA(dst, b, h) do { _Pragma("unroll") for (int m = 0; m < 4; ++m) _Pragma("unroll") for (int k = 0; k < 2; ++k) dst[m][k] = *(const PG8_LAS bf16x8*)(lds + PG8_SA(b, h) + aoff + m * 2048 + k * 1024); } while (0)
; #define PG8_LDB(dst, b, h) do { _Pragma("unroll") for (int n = 0; n < 2; ++n) _Pragma("unroll") for (int k = 0; k < 2; ++k) dst[n][k] = *(const PG8_LAS bf16x8*)(lds + PG8_SB(b, h) + boff + n * 2048 + k * 1024); } while (0)
; #define PG8_LDX(pb, tp) do { _Pragma("unroll") for (int k = 0; k < 2; ++k) Ax[k] = *(const PG8_LAS bf16x8*)(lds + xoff + (pb) * 4096 + (tp) * 128 + k * 64); } while (0)
; #define PG8_MMA(ai, bj, At, Bt) do { __builtin_amdgcn_s_setprio(1); _Pragma("unroll") for (int m = 0; m < 4; ++m) _Pragma("unroll") for (int n = 0; n < 2; ++n) _Pragma("unroll") for (int k = 0; k < 2; ++k) \
;         acc[ai][bj][m][n] = __builtin_amdgcn_mfma_f32_16x16x32_bf16(Bt[n][k], At[m][k], acc[ai][bj][m][n], 0, 0, 0); __builtin_amdgcn_s_setprio(0); } while (0)
; #define PG8_WAIT_V(n) asm volatile("s_waitcnt vmcnt(" #n ")" ::: "memory")
; #define PG8_WAIT_L(n) asm volatile("s_waitcnt lgkmcnt(" #n ")" ::: "memory")
; #define PG8_BAR __builtin_amdgcn_s_barrier()
; #define PG8_SCHED __builtin_amdgcn_sched_barrier(0)
; template <class Epi, class Sched, bool HM = false>
; __device__ __forceinline__ void gemm_phase(PG8_LAS unsigned char* lds, const Gemm g, const Sched& S, const Epi& E) {
;     ...
;             PG8_LDB(B0, 0, 0); PG8_LDB(B1, 0, 1); PG8_SCHED; PG8_LDA(At, 0, 0); if (hasx) PG8_LDX(pb, 0); PG8_STAGE(PG8_SA(1, 1), a1 + hstepA, voffA); PG8_STAGEX(pb ^ 1, a2 + xstep);
;             PG8_WAIT_V(9); PG8_WAIT_L(0); PG8_BAR; PG8_MMA(0, 0, At, B0); PG8_MMA(0, 1, At, B1); if (hasx) PG8_MMAX(); PG8_BAR; PG8_SCHED;
;             if (!HM) PG8_LDA(At, 0, 1); PG8_STAGE(PG8_SB(0, 0), b2, voffB); PG8_STAGE(PG8_SB(0, 1), b2 + hstepB, voffB); PG8_STAGE(PG8_SA(0, 0), a2, voffA);
;             PG8_WAIT_V(9); PG8_WAIT_L(0); PG8_BAR; if (!HM) { PG8_MMA(1, 0, At, B0); PG8_MMA(1, 1, At, B1); } PG8_BAR; PG8_SCHED;
.LBB0_258:
	s_add_u32 s34, s34, 0x80000
	s_addc_u32 s35, s35, 0
	s_mov_b32 s21, m0
	s_mov_b32 m0, s59
	s_nop 0
	global_load_lds_dwordx4 v225, s[34:35]
	s_mov_b32 m0, s21
	s_nop 0
	s_mov_b32 s21, m0
	s_mov_b32 m0, s83
	s_nop 0
	global_load_lds_dwordx4 v227, s[34:35]
	s_mov_b32 m0, s21
	s_add_u32 s34, s92, 0x100000
	s_addc_u32 s35, s93, 0
	s_xor_b32 s20, s20, 0x21400
	s_add_i32 s20, s29, s20
	s_mov_b32 s21, m0
	s_mov_b32 m0, s20
	s_nop 0
	global_load_lds_dwordx4 v229, s[34:35]
	s_mov_b32 m0, s21
	s_waitcnt vmcnt(9)
	s_waitcnt lgkmcnt(0)
	s_barrier
	s_setprio 1
	s_waitcnt lgkmcnt(7)
	v_mfma_f32_16x16x32_bf16 v[146:149], v[166:169], v[206:209], v[146:149]
	v_mfma_f32_16x16x32_bf16 v[142:145], v[174:177], v[206:209], v[142:145]
	s_waitcnt lgkmcnt(5)
	v_mfma_f32_16x16x32_bf16 v[138:141], v[166:169], v[198:201], v[138:141]
	v_mfma_f32_16x16x32_bf16 v[130:133], v[174:177], v[198:201], v[130:133]
	s_waitcnt lgkmcnt(3)
	v_mfma_f32_16x16x32_bf16 v[122:125], v[166:169], v[190:193], v[122:125]
	v_mfma_f32_16x16x32_bf16 v[114:117], v[174:177], v[190:193], v[114:117]
	s_waitcnt lgkmcnt(1)
	v_mfma_f32_16x16x32_bf16 v[106:109], v[166:169], v[182:185], v[106:109]
	v_mfma_f32_16x16x32_bf16 v[98:101], v[174:177], v[182:185], v[98:101]
	v_mfma_f32_16x16x32_bf16 v[146:149], v[170:173], v[210:213], v[146:149]
	v_mfma_f32_16x16x32_bf16 v[142:145], v[178:181], v[210:213], v[142:145]
	v_mfma_f32_16x16x32_bf16 v[138:141], v[170:173], v[202:205], v[138:141]
	v_mfma_f32_16x16x32_bf16 v[130:133], v[178:181], v[202:205], v[130:133]
	v_mfma_f32_16x16x32_bf16 v[122:125], v[170:173], v[194:197], v[122:125]
	v_mfma_f32_16x16x32_bf16 v[114:117], v[178:181], v[194:197], v[114:117]
	s_waitcnt lgkmcnt(0)
	v_mfma_f32_16x16x32_bf16 v[106:109], v[170:173], v[186:189], v[106:109]
	v_mfma_f32_16x16x32_bf16 v[98:101], v[178:181], v[186:189], v[98:101]
	s_setprio 0
	s_setprio 1
	v_mfma_f32_16x16x32_bf16 v[134:137], v[150:153], v[206:209], v[134:137]
	v_mfma_f32_16x16x32_bf16 v[126:129], v[158:161], v[206:209], v[126:129]
	v_mfma_f32_16x16x32_bf16 v[118:121], v[150:153], v[198:201], v[118:121]
	v_mfma_f32_16x16x32_bf16 v[110:113], v[158:161], v[198:201], v[110:113]
	v_mfma_f32_16x16x32_bf16 v[102:105], v[150:153], v[190:193], v[102:105]
	v_mfma_f32_16x16x32_bf16 v[94:97], v[158:161], v[190:193], v[94:97]
	v_mfma_f32_16x16x32_bf16 v[90:93], v[150:153], v[182:185], v[90:93]
	v_mfma_f32_16x16x32_bf16 v[86:89], v[158:161], v[182:185], v[86:89]
	v_mfma_f32_16x16x32_bf16 v[134:137], v[154:157], v[210:213], v[134:137]
	v_mfma_f32_16x16x32_bf16 v[126:129], v[162:165], v[210:213], v[126:129]
	v_mfma_f32_16x16x32_bf16 v[118:121], v[154:157], v[202:205], v[118:121]
	v_mfma_f32_16x16x32_bf16 v[110:113], v[162:165], v[202:205], v[110:113]
	v_mfma_f32_16x16x32_bf16 v[102:105], v[154:157], v[194:197], v[102:105]
	v_mfma_f32_16x16x32_bf16 v[94:97], v[162:165], v[194:197], v[94:97]
	v_mfma_f32_16x16x32_bf16 v[90:93], v[154:157], v[186:189], v[90:93]
	v_mfma_f32_16x16x32_bf16 v[86:89], v[162:165], v[186:189], v[86:89]
	s_setprio 0
	v_cndmask_b32_e64 v4, 0, 1, s[76:77]
	s_and_b64 vcc, exec, s[42:43]
	v_cmp_ne_u32_e64 s[44:45], 1, v4
	s_cbranch_vccnz .LBB0_264
	s_and_b64 vcc, exec, s[44:45]
	s_mov_b64 s[20:21], -1
	s_cbranch_vccnz .LBB0_261
	v_mfma_f32_16x16x32_bf16 v[18:21], v[174:177], v[6:9], v[18:21]
	s_mov_b64 s[20:21], 0
	v_mfma_f32_16x16x32_bf16 v[14:17], v[158:161], v[6:9], v[14:17]
	v_mfma_f32_16x16x32_bf16 v[18:21], v[178:181], v[10:13], v[18:21]
	v_mfma_f32_16x16x32_bf16 v[14:17], v[162:165], v[10:13], v[14:17]
.LBB0_261:
	s_andn2_b64 vcc, exec, s[20:21]
	s_cbranch_vccnz .LBB0_263
	v_mfma_f32_16x16x32_bf16 v[18:21], v[166:169], v[6:9], v[18:21]
	v_mfma_f32_16x16x32_bf16 v[14:17], v[150:153], v[6:9], v[14:17]
	v_mfma_f32_16x16x32_bf16 v[18:21], v[170:173], v[10:13], v[18:21]
	v_mfma_f32_16x16x32_bf16 v[14:17], v[154:157], v[10:13], v[14:17]
.LBB0_263:
.LBB0_264:
	s_barrier
	ds_read_b128 v[182:185], v235 offset:16384
	ds_read_b128 v[186:189], v235 offset:17408
	ds_read_b128 v[190:193], v235 offset:18432
	ds_read_b128 v[194:197], v235 offset:19456
	ds_read_b128 v[198:201], v235 offset:20480
	ds_read_b128 v[202:205], v235 offset:21504
	ds_read_b128 v[206:209], v235 offset:22528
	ds_read_b128 v[210:213], v235 offset:23552
	s_mov_b32 s20, m0
	s_mov_b32 m0, s18
	s_nop 0
	global_load_lds_dwordx4 v226, s[8:9]
	s_mov_b32 m0, s20
	s_nop 0
	s_mov_b32 s20, m0
	s_mov_b32 m0, s19
	s_nop 0
	global_load_lds_dwordx4 v228, s[8:9]
	s_mov_b32 m0, s20
	s_add_u32 s8, s8, 0x20000
	s_addc_u32 s9, s9, 0
	s_mov_b32 s20, m0
	s_mov_b32 m0, s24
	s_nop 0
	global_load_lds_dwordx4 v226, s[8:9]
	s_mov_b32 m0, s20
	s_nop 0
	s_mov_b32 s20, m0
	s_mov_b32 m0, s25
	s_nop 0
	global_load_lds_dwordx4 v228, s[8:9]
	s_mov_b32 m0, s20
	s_mov_b32 s8, m0
	s_mov_b32 m0, s17
	s_nop 0
	global_load_lds_dwordx4 v225, s[92:93]
	s_mov_b32 m0, s8
	s_nop 0
	s_mov_b32 s8, m0
	s_mov_b32 m0, s28
	s_nop 0
	global_load_lds_dwordx4 v227, s[92:93]
	s_mov_b32 m0, s8
	s_waitcnt vmcnt(9)
	s_waitcnt lgkmcnt(0)
	s_barrier
; #define PG8_STAGE(bufoff, gbase, voff) do { _Pragma("unroll") for (int _i = 0; _i < 2; ++_i) glds16_s((voff)[_i], (const void*)(gbase), ldsbase + (unsigned)((bufoff) + _i * 8192) + ldsw); } while (0)
; #define PG8_LDA(dst, b, h) do { _Pragma("unroll") for (int m = 0; m < 4; ++m) _Pragma("unroll") for (int k = 0; k < 2; ++k) dst[m][k] = *(const PG8_LAS bf16x8*)(lds + PG8_SA(b, h) + aoff + m * 2048 + k * 1024); } while (0)
; #define PG8_LDB(dst, b, h) do { _Pragma("unroll") for (int n = 0; n < 2; ++n) _Pragma("unroll") for (int k = 0; k < 2; ++k) dst[n][k] = *(const PG8_LAS bf16x8*)(lds + PG8_SB(b, h) + boff + n * 2048 + k * 1024); } while (0)
; #define PG8_LDX(pb, tp) do { _Pragma("unroll") for (int k = 0; k < 2; ++k) Ax[k] = *(const PG8_LAS bf16x8*)(lds + xoff + (pb) * 4096 + (tp) * 128 + k * 64); } while (0)
; #define PG8_MMA(ai, bj, At, Bt) do { __builtin_amdgcn_s_setprio(1); _Pragma("unroll") for (int m = 0; m < 4; ++m) _Pragma("unroll") for (int n = 0; n < 2; ++n) _Pragma("unroll") for (int k = 0; k < 2; ++k) \
;         acc[ai][bj][m][n] = __builtin_amdgcn_mfma_f32_16x16x32_bf16(Bt[n][k], At[m][k], acc[ai][bj][m][n], 0, 0, 0); __builtin_amdgcn_s_setprio(0); } while (0)
; #define PG8_WAIT_V(n) asm volatile("s_waitcnt vmcnt(" #n ")" ::: "memory")
; #define PG8_WAIT_L(n) asm volatile("s_waitcnt lgkmcnt(" #n ")" ::: "memory")
; #define PG8_BAR __builtin_amdgcn_s_barrier()
; #define PG8_SCHED __builtin_amdgcn_sched_barrier(0)
; template <class Epi, class Sched, bool HM = false>
; __device__ __forceinline__ void gemm_phase(PG8_LAS unsigned char* lds, const Gemm g, const Sched& S, const Epi& E) {
;     ...
;             PG8_WAIT_V(9); PG8_WAIT_L(0); PG8_BAR; if (!HM) { PG8_MMA(1, 0, At, B0); PG8_MMA(1, 1, At, B1); } PG8_BAR; PG8_SCHED;
;             PG8_LDB(B0, 1, 0); PG8_LDB(B1, 1, 1); PG8_SCHED; PG8_LDA(At, 1, 0); if (hasx) PG8_LDX(pb, 1); PG8_STAGE(PG8_SA(0, 1), a2 + hstepA, voffA);
;             PG8_WAIT_V(9); PG8_WAIT_L(0); PG8_BAR; PG8_MMA(0, 0, At, B0); PG8_MMA(0, 1, At, B1); if (hasx) PG8_MMAX(); PG8_BAR; PG8_SCHED;
;             if (!HM) PG8_LDA(At, 1, 1); PG8_STAGE(PG8_SB(1, 0), b3, voffB); PG8_STAGE(PG8_SB(1, 1), b3 + hstepB, voffB); PG8_STAGE(PG8_SA(1, 0), a3, voffA);
;             PG8_WAIT_V(8); PG8_WAIT_L(0); PG8_BAR; if (!HM) { PG8_MMA(1, 0, At, B0); PG8_MMA(1, 1, At, B1); } PG8_BAR; PG8_SCHED;
	s_setprio 1
	s_waitcnt lgkmcnt(7)
	v_mfma_f32_16x16x32_bf16 v[82:85], v[166:169], v[182:185], v[82:85]
	v_mfma_f32_16x16x32_bf16 v[78:81], v[174:177], v[182:185], v[78:81]
	s_waitcnt lgkmcnt(5)
	v_mfma_f32_16x16x32_bf16 v[74:77], v[166:169], v[190:193], v[74:77]
	v_mfma_f32_16x16x32_bf16 v[66:69], v[174:177], v[190:193], v[66:69]
	s_waitcnt lgkmcnt(3)
	v_mfma_f32_16x16x32_bf16 v[58:61], v[166:169], v[198:201], v[58:61]
	v_mfma_f32_16x16x32_bf16 v[50:53], v[174:177], v[198:201], v[50:53]
	s_waitcnt lgkmcnt(1)
	v_mfma_f32_16x16x32_bf16 v[42:45], v[166:169], v[206:209], v[42:45]
	v_mfma_f32_16x16x32_bf16 v[34:37], v[174:177], v[206:209], v[34:37]
	v_mfma_f32_16x16x32_bf16 v[82:85], v[170:173], v[186:189], v[82:85]
	v_mfma_f32_16x16x32_bf16 v[78:81], v[178:181], v[186:189], v[78:81]
	v_mfma_f32_16x16x32_bf16 v[74:77], v[170:173], v[194:197], v[74:77]
	v_mfma_f32_16x16x32_bf16 v[66:69], v[178:181], v[194:197], v[66:69]
	v_mfma_f32_16x16x32_bf16 v[58:61], v[170:173], v[202:205], v[58:61]
	v_mfma_f32_16x16x32_bf16 v[50:53], v[178:181], v[202:205], v[50:53]
	s_waitcnt lgkmcnt(0)
	v_mfma_f32_16x16x32_bf16 v[42:45], v[170:173], v[210:213], v[42:45]
	v_mfma_f32_16x16x32_bf16 v[34:37], v[178:181], v[210:213], v[34:37]
	s_setprio 0
	s_setprio 1
	v_mfma_f32_16x16x32_bf16 v[70:73], v[150:153], v[182:185], v[70:73]
	v_mfma_f32_16x16x32_bf16 v[62:65], v[158:161], v[182:185], v[62:65]
	v_mfma_f32_16x16x32_bf16 v[54:57], v[150:153], v[190:193], v[54:57]
	v_mfma_f32_16x16x32_bf16 v[46:49], v[158:161], v[190:193], v[46:49]
	v_mfma_f32_16x16x32_bf16 v[38:41], v[150:153], v[198:201], v[38:41]
	v_mfma_f32_16x16x32_bf16 v[30:33], v[158:161], v[198:201], v[30:33]
	v_mfma_f32_16x16x32_bf16 v[26:29], v[150:153], v[206:209], v[26:29]
	v_mfma_f32_16x16x32_bf16 v[22:25], v[158:161], v[206:209], v[22:25]
	v_mfma_f32_16x16x32_bf16 v[70:73], v[154:157], v[186:189], v[70:73]
	v_mfma_f32_16x16x32_bf16 v[62:65], v[162:165], v[186:189], v[62:65]
	v_mfma_f32_16x16x32_bf16 v[54:57], v[154:157], v[194:197], v[54:57]
	v_mfma_f32_16x16x32_bf16 v[46:49], v[162:165], v[194:197], v[46:49]
	v_mfma_f32_16x16x32_bf16 v[38:41], v[154:157], v[202:205], v[38:41]
	v_mfma_f32_16x16x32_bf16 v[30:33], v[162:165], v[202:205], v[30:33]
	v_mfma_f32_16x16x32_bf16 v[26:29], v[154:157], v[210:213], v[26:29]
	v_mfma_f32_16x16x32_bf16 v[22:25], v[162:165], v[210:213], v[22:25]
	s_setprio 0
	s_barrier
	v_add_u32_e32 v4, 0x18000, v234
	ds_read_b128 v[166:169], v4
	ds_read_b128 v[170:173], v4 offset:1024
	ds_read_b128 v[174:177], v4 offset:2048
	ds_read_b128 v[178:181], v4 offset:3072
	v_add_u32_e32 v4, 0x1c000, v234
	ds_read_b128 v[150:153], v4
	ds_read_b128 v[154:157], v4 offset:1024
	ds_read_b128 v[158:161], v4 offset:2048
	ds_read_b128 v[162:165], v4 offset:3072
	ds_read_b128 v[206:209], v235 offset:32768
	ds_read_b128 v[210:213], v235 offset:33792
	ds_read_b128 v[198:201], v235 offset:34816
	ds_read_b128 v[202:205], v235 offset:35840
	ds_read_b128 v[190:193], v235 offset:36864
	ds_read_b128 v[194:197], v235 offset:37888
	ds_read_b128 v[182:185], v235 offset:38912
	ds_read_b128 v[186:189], v235 offset:39936
	s_and_b64 vcc, exec, s[42:43]
	s_cbranch_vccnz .LBB0_266
	ds_read_b128 v[6:9], v2 offset:128
	ds_read_b128 v[10:13], v2 offset:192
.LBB0_266:
	s_add_u32 s8, s92, 0x80000
	s_addc_u32 s9, s93, 0
	s_mov_b32 s20, m0
	s_mov_b32 m0, s30
	s_nop 0
	global_load_lds_dwordx4 v225, s[8:9]
	s_mov_b32 m0, s20
	s_nop 0
	s_mov_b32 s20, m0
	s_mov_b32 m0, s31
	s_nop 0
	global_load_lds_dwordx4 v227, s[8:9]
	s_mov_b32 m0, s20
	s_waitcnt vmcnt(9)
	s_waitcnt lgkmcnt(0)
	s_barrier
	s_setprio 1
	s_waitcnt lgkmcnt(7)
	v_mfma_f32_16x16x32_bf16 v[146:149], v[166:169], v[206:209], v[146:149]
	v_mfma_f32_16x16x32_bf16 v[142:145], v[174:177], v[206:209], v[142:145]
	s_waitcnt lgkmcnt(5)
	v_mfma_f32_16x16x32_bf16 v[138:141], v[166:169], v[198:201], v[138:141]
	v_mfma_f32_16x16x32_bf16 v[130:133], v[174:177], v[198:201], v[130:133]
	s_waitcnt lgkmcnt(3)
	v_mfma_f32_16x16x32_bf16 v[122:125], v[166:169], v[190:193], v[122:125]
	v_mfma_f32_16x16x32_bf16 v[114:117], v[174:177], v[190:193], v[114:117]
	s_waitcnt lgkmcnt(1)
	v_mfma_f32_16x16x32_bf16 v[106:109], v[166:169], v[182:185], v[106:109]
	v_mfma_f32_16x16x32_bf16 v[98:101], v[174:177], v[182:185], v[98:101]
	v_mfma_f32_16x16x32_bf16 v[146:149], v[170:173], v[210:213], v[146:149]
	v_mfma_f32_16x16x32_bf16 v[142:145], v[178:181], v[210:213], v[142:145]
	v_mfma_f32_16x16x32_bf16 v[138:141], v[170:173], v[202:205], v[138:141]
	v_mfma_f32_16x16x32_bf16 v[130:133], v[178:181], v[202:205], v[130:133]
	v_mfma_f32_16x16x32_bf16 v[122:125], v[170:173], v[194:197], v[122:125]
	v_mfma_f32_16x16x32_bf16 v[114:117], v[178:181], v[194:197], v[114:117]
	s_waitcnt lgkmcnt(0)
	v_mfma_f32_16x16x32_bf16 v[106:109], v[170:173], v[186:189], v[106:109]
	v_mfma_f32_16x16x32_bf16 v[98:101], v[178:181], v[186:189], v[98:101]
	s_setprio 0
	s_setprio 1
	v_mfma_f32_16x16x32_bf16 v[134:137], v[150:153], v[206:209], v[134:137]
	v_mfma_f32_16x16x32_bf16 v[126:129], v[158:161], v[206:209], v[126:129]
	v_mfma_f32_16x16x32_bf16 v[118:121], v[150:153], v[198:201], v[118:121]
	v_mfma_f32_16x16x32_bf16 v[110:113], v[158:161], v[198:201], v[110:113]
	v_mfma_f32_16x16x32_bf16 v[102:105], v[150:153], v[190:193], v[102:105]
	v_mfma_f32_16x16x32_bf16 v[94:97], v[158:161], v[190:193], v[94:97]
	v_mfma_f32_16x16x32_bf16 v[90:93], v[150:153], v[182:185], v[90:93]
	v_mfma_f32_16x16x32_bf16 v[86:89], v[158:161], v[182:185], v[86:89]
	v_mfma_f32_16x16x32_bf16 v[134:137], v[154:157], v[210:213], v[134:137]
	v_mfma_f32_16x16x32_bf16 v[126:129], v[162:165], v[210:213], v[126:129]
	v_mfma_f32_16x16x32_bf16 v[118:121], v[154:157], v[202:205], v[118:121]
	v_mfma_f32_16x16x32_bf16 v[110:113], v[162:165], v[202:205], v[110:113]
	v_mfma_f32_16x16x32_bf16 v[102:105], v[154:157], v[194:197], v[102:105]
	v_mfma_f32_16x16x32_bf16 v[94:97], v[162:165], v[194:197], v[94:97]
	v_mfma_f32_16x16x32_bf16 v[90:93], v[154:157], v[186:189], v[90:93]
	v_mfma_f32_16x16x32_bf16 v[86:89], v[162:165], v[186:189], v[86:89]
	s_setprio 0
	s_and_b64 vcc, exec, s[42:43]
	s_cbranch_vccnz .LBB0_255
	s_and_b64 vcc, exec, s[44:45]
	s_mov_b64 s[8:9], -1
	s_cbranch_vccnz .LBB0_269
	v_mfma_f32_16x16x32_bf16 v[18:21], v[174:177], v[6:9], v[18:21]
	s_mov_b64 s[8:9], 0
	v_mfma_f32_16x16x32_bf16 v[14:17], v[158:161], v[6:9], v[14:17]
	v_mfma_f32_16x16x32_bf16 v[18:21], v[178:181], v[10:13], v[18:21]
	v_mfma_f32_16x16x32_bf16 v[14:17], v[162:165], v[10:13], v[14:17]
.LBB0_269:
	s_andn2_b64 vcc, exec, s[8:9]
	s_cbranch_vccnz .LBB0_254
	v_mfma_f32_16x16x32_bf16 v[18:21], v[166:169], v[6:9], v[18:21]
	v_mfma_f32_16x16x32_bf16 v[14:17], v[150:153], v[6:9], v[14:17]
	v_mfma_f32_16x16x32_bf16 v[18:21], v[170:173], v[10:13], v[18:21]
	v_mfma_f32_16x16x32_bf16 v[14:17], v[154:157], v[10:13], v[14:17]
	s_branch .LBB0_254

; #define PG8_STAGE(bufoff, gbase, voff) do { _Pragma("unroll") for (int _i = 0; _i < 2; ++_i) glds16_s((voff)[_i], (const void*)(gbase), ldsbase + (unsigned)((bufoff) + _i * 8192) + ldsw); } while (0)
; #define PG8_LDA(dst, b, h) do { _Pragma("unroll") for (int m = 0; m < 4; ++m) _Pragma("unroll") for (int k = 0; k < 2; ++k) dst[m][k] = *(const PG8_LAS bf16x8*)(lds + PG8_SA(b, h) + aoff + m * 2048 + k * 1024); } while (0)
; #define PG8_MMA(ai, bj, At, Bt) do { __builtin_amdgcn_s_setprio(1); _Pragma("unroll") for (int m = 0; m < 4; ++m) _Pragma("unroll") for (int n = 0; n < 2; ++n) _Pragma("unroll") for (int k = 0; k < 2; ++k) \
;         acc[ai][bj][m][n] = __builtin_amdgcn_mfma_f32_16x16x32_bf16(Bt[n][k], At[m][k], acc[ai][bj][m][n], 0, 0, 0); __builtin_amdgcn_s_setprio(0); } while (0)
; #define PG8_WAIT_V(n) asm volatile("s_waitcnt vmcnt(" #n ")" ::: "memory")
; #define PG8_WAIT_L(n) asm volatile("s_waitcnt lgkmcnt(" #n ")" ::: "memory")
; #define PG8_BAR __builtin_amdgcn_s_barrier()
; #define PG8_SCHED __builtin_amdgcn_sched_barrier(0)
; template <class Epi, class Sched, bool HM = false>
; __device__ __forceinline__ void gemm_phase(PG8_LAS unsigned char* lds, const Gemm g, const Sched& S, const Epi& E) {
;     ...
;             if (!HM) PG8_LDA(At, 1, 1); PG8_STAGE(PG8_SB(1, 0), b3, voffB); PG8_STAGE(PG8_SB(1, 1), b3 + hstepB, voffB); PG8_STAGE(PG8_SA(1, 0), a3, voffA);
;             PG8_WAIT_V(8); PG8_WAIT_L(0); PG8_BAR; if (!HM) { PG8_MMA(1, 0, At, B0); PG8_MMA(1, 1, At, B1); } PG8_BAR; PG8_SCHED;
;         }
.LBB0_532:
.LBB0_533:
	s_barrier
	ds_read_b128 v[182:185], v235 offset:49152
	ds_read_b128 v[186:189], v235 offset:50176
	ds_read_b128 v[190:193], v235 offset:51200
	ds_read_b128 v[194:197], v235 offset:52224
	ds_read_b128 v[198:201], v235 offset:53248
	ds_read_b128 v[202:205], v235 offset:54272
	ds_read_b128 v[206:209], v235 offset:55296
	ds_read_b128 v[210:213], v235 offset:56320
	s_mov_b32 s8, m0
	s_mov_b32 m0, s37
	s_nop 0
	global_load_lds_dwordx4 v226, s[6:7]
	s_mov_b32 m0, s8
	s_nop 0
	s_mov_b32 s8, m0
	s_mov_b32 m0, s51
	s_nop 0
	global_load_lds_dwordx4 v228, s[6:7]
	s_mov_b32 m0, s8
	s_add_u32 s6, s6, 0x80000
	s_addc_u32 s7, s7, 0
	s_mov_b32 s8, m0
	s_mov_b32 m0, s58
	s_nop 0
	global_load_lds_dwordx4 v226, s[6:7]
	s_mov_b32 m0, s8
	s_nop 0
	s_mov_b32 s8, m0
	s_mov_b32 m0, s59
	s_nop 0
	global_load_lds_dwordx4 v228, s[6:7]
	s_mov_b32 m0, s8
	s_mov_b32 s6, m0
	s_mov_b32 m0, s52
	s_nop 0
	global_load_lds_dwordx4 v225, s[4:5]
	s_mov_b32 m0, s6
	s_nop 0
	s_mov_b32 s6, m0
	s_mov_b32 m0, s57
	s_nop 0
	global_load_lds_dwordx4 v227, s[4:5]
	s_mov_b32 m0, s6
	s_waitcnt vmcnt(8)
	s_waitcnt lgkmcnt(0)
	s_barrier
	s_setprio 1
	s_waitcnt lgkmcnt(7)
	v_mfma_f32_16x16x32_bf16 v[82:85], v[166:169], v[182:185], v[82:85]
	v_mfma_f32_16x16x32_bf16 v[78:81], v[174:177], v[182:185], v[78:81]
	s_waitcnt lgkmcnt(5)
	v_mfma_f32_16x16x32_bf16 v[74:77], v[166:169], v[190:193], v[74:77]
	v_mfma_f32_16x16x32_bf16 v[66:69], v[174:177], v[190:193], v[66:69]
	s_waitcnt lgkmcnt(3)
	v_mfma_f32_16x16x32_bf16 v[58:61], v[166:169], v[198:201], v[58:61]
	v_mfma_f32_16x16x32_bf16 v[50:53], v[174:177], v[198:201], v[50:53]
	s_waitcnt lgkmcnt(1)
	v_mfma_f32_16x16x32_bf16 v[42:45], v[166:169], v[206:209], v[42:45]
	v_mfma_f32_16x16x32_bf16 v[34:37], v[174:177], v[206:209], v[34:37]
	v_mfma_f32_16x16x32_bf16 v[82:85], v[170:173], v[186:189], v[82:85]
	v_mfma_f32_16x16x32_bf16 v[78:81], v[178:181], v[186:189], v[78:81]
	v_mfma_f32_16x16x32_bf16 v[74:77], v[170:173], v[194:197], v[74:77]
	v_mfma_f32_16x16x32_bf16 v[66:69], v[178:181], v[194:197], v[66:69]
	v_mfma_f32_16x16x32_bf16 v[58:61], v[170:173], v[202:205], v[58:61]
	v_mfma_f32_16x16x32_bf16 v[50:53], v[178:181], v[202:205], v[50:53]
	s_waitcnt lgkmcnt(0)
	v_mfma_f32_16x16x32_bf16 v[42:45], v[170:173], v[210:213], v[42:45]
	v_mfma_f32_16x16x32_bf16 v[34:37], v[178:181], v[210:213], v[34:37]
	s_setprio 0
	s_setprio 1
	v_mfma_f32_16x16x32_bf16 v[70:73], v[150:153], v[182:185], v[70:73]
	v_mfma_f32_16x16x32_bf16 v[62:65], v[158:161], v[182:185], v[62:65]
	v_mfma_f32_16x16x32_bf16 v[54:57], v[150:153], v[190:193], v[54:57]
	v_mfma_f32_16x16x32_bf16 v[46:49], v[158:161], v[190:193], v[46:49]
	v_mfma_f32_16x16x32_bf16 v[38:41], v[150:153], v[198:201], v[38:41]
	v_mfma_f32_16x16x32_bf16 v[30:33], v[158:161], v[198:201], v[30:33]
	v_mfma_f32_16x16x32_bf16 v[26:29], v[150:153], v[206:209], v[26:29]
	v_mfma_f32_16x16x32_bf16 v[22:25], v[158:161], v[206:209], v[22:25]
	v_mfma_f32_16x16x32_bf16 v[70:73], v[154:157], v[186:189], v[70:73]
	v_mfma_f32_16x16x32_bf16 v[62:65], v[162:165], v[186:189], v[62:65]
	v_mfma_f32_16x16x32_bf16 v[54:57], v[154:157], v[194:197], v[54:57]
	v_mfma_f32_16x16x32_bf16 v[46:49], v[162:165], v[194:197], v[46:49]
	v_mfma_f32_16x16x32_bf16 v[38:41], v[154:157], v[202:205], v[38:41]
	v_mfma_f32_16x16x32_bf16 v[30:33], v[162:165], v[202:205], v[30:33]
	v_mfma_f32_16x16x32_bf16 v[26:29], v[154:157], v[210:213], v[26:29]
	v_mfma_f32_16x16x32_bf16 v[22:25], v[162:165], v[210:213], v[22:25]
	s_setprio 0
	s_barrier
	s_add_i32 s23, s23, 2
	s_addk_i32 s22, 0x1000
	s_add_u32 s38, s38, 0x100
	s_addc_u32 s39, s39, 0
	s_add_u32 s27, s27, 0x100
	s_addc_u32 s82, s82, 0
	s_cmp_gt_u32 s23, 29
	s_cbranch_scc1 .LBB0_549

; #define PG8_STAGE(bufoff, gbase, voff) do { _Pragma("unroll") for (int _i = 0; _i < 2; ++_i) glds16_s((voff)[_i], (const void*)(gbase), ldsbase + (unsigned)((bufoff) + _i * 8192) + ldsw); } while (0)
; #define PG8_STAGEX(pb, gbase) glds16_s(voffX, (const void*)(gbase), ldsbase + (unsigned)(XOFF + (pb) * 4096) + ldsx)
; #define PG8_LDA(dst, b, h) do { _Pragma("unroll") for (int m = 0; m < 4; ++m) _Pragma("unroll") for (int k = 0; k < 2; ++k) dst[m][k] = *(const PG8_LAS bf16x8*)(lds + PG8_SA(b, h) + aoff + m * 2048 + k * 1024); } while (0)
; #define PG8_LDB(dst, b, h) do { _Pragma("unroll") for (int n = 0; n < 2; ++n) _Pragma("unroll") for (int k = 0; k < 2; ++k) dst[n][k] = *(const PG8_LAS bf16x8*)(lds + PG8_SB(b, h) + boff + n * 2048 + k * 1024); } while (0)
; #define PG8_LDX(pb, tp) do { _Pragma("unroll") for (int k = 0; k < 2; ++k) Ax[k] = *(const PG8_LAS bf16x8*)(lds + xoff + (pb) * 4096 + (tp) * 128 + k * 64); } while (0)
; #define PG8_MMA(ai, bj, At, Bt) do { __builtin_amdgcn_s_setprio(1); _Pragma("unroll") for (int m = 0; m < 4; ++m) _Pragma("unroll") for (int n = 0; n < 2; ++n) _Pragma("unroll") for (int k = 0; k < 2; ++k) \
;         acc[ai][bj][m][n] = __builtin_amdgcn_mfma_f32_16x16x32_bf16(Bt[n][k], At[m][k], acc[ai][bj][m][n], 0, 0, 0); __builtin_amdgcn_s_setprio(0); } while (0)
; #define PG8_WAIT_V(n) asm volatile("s_waitcnt vmcnt(" #n ")" ::: "memory")
; #define PG8_WAIT_L(n) asm volatile("s_waitcnt lgkmcnt(" #n ")" ::: "memory")
; #define PG8_BAR __builtin_amdgcn_s_barrier()
; #define PG8_SCHED __builtin_amdgcn_sched_barrier(0)
; template <class Epi, class Sched, bool HM = false>
; __device__ __forceinline__ void gemm_phase(PG8_LAS unsigned char* lds, const Gemm g, const Sched& S, const Epi& E) {
;     ...
;             PG8_LDB(B0, 0, 0); PG8_LDB(B1, 0, 1); PG8_SCHED; PG8_LDA(At, 0, 0); if (hasx) PG8_LDX(pb, 0); PG8_STAGE(PG8_SA(1, 1), a1 + hstepA, voffA); PG8_STAGEX(pb ^ 1, a2 + xstep);
;             PG8_WAIT_V(9); PG8_WAIT_L(0); PG8_BAR; PG8_MMA(0, 0, At, B0); PG8_MMA(0, 1, At, B1); if (hasx) PG8_MMAX(); PG8_BAR; PG8_SCHED;
.LBB0_536:
	s_add_u32 s34, s34, 0x80000
	s_addc_u32 s35, s35, 0
	s_mov_b32 s21, m0
	s_mov_b32 m0, s83
	s_nop 0
	global_load_lds_dwordx4 v225, s[34:35]
	s_mov_b32 m0, s21
	s_nop 0
	s_mov_b32 s21, m0
	s_mov_b32 m0, s88
	s_nop 0
	global_load_lds_dwordx4 v227, s[34:35]
	s_mov_b32 m0, s21
	s_add_u32 s34, s94, 0x100000
	s_addc_u32 s35, s95, 0
	s_xor_b32 s20, s20, 0x21400
	s_add_i32 s20, s30, s20
	s_mov_b32 s21, m0
	s_mov_b32 m0, s20
	s_nop 0
	global_load_lds_dwordx4 v229, s[34:35]
	s_mov_b32 m0, s21
	s_waitcnt vmcnt(9)
	s_waitcnt lgkmcnt(0)
	s_barrier
	s_setprio 1
	s_waitcnt lgkmcnt(7)
	v_mfma_f32_16x16x32_bf16 v[146:149], v[166:169], v[206:209], v[146:149]
	v_mfma_f32_16x16x32_bf16 v[142:145], v[174:177], v[206:209], v[142:145]
	s_waitcnt lgkmcnt(5)
	v_mfma_f32_16x16x32_bf16 v[138:141], v[166:169], v[198:201], v[138:141]
	v_mfma_f32_16x16x32_bf16 v[130:133], v[174:177], v[198:201], v[130:133]
	s_waitcnt lgkmcnt(3)
	v_mfma_f32_16x16x32_bf16 v[122:125], v[166:169], v[190:193], v[122:125]
	v_mfma_f32_16x16x32_bf16 v[114:117], v[174:177], v[190:193], v[114:117]
	s_waitcnt lgkmcnt(1)
	v_mfma_f32_16x16x32_bf16 v[106:109], v[166:169], v[182:185], v[106:109]
	v_mfma_f32_16x16x32_bf16 v[98:101], v[174:177], v[182:185], v[98:101]
	v_mfma_f32_16x16x32_bf16 v[146:149], v[170:173], v[210:213], v[146:149]
	v_mfma_f32_16x16x32_bf16 v[142:145], v[178:181], v[210:213], v[142:145]
	v_mfma_f32_16x16x32_bf16 v[138:141], v[170:173], v[202:205], v[138:141]
	v_mfma_f32_16x16x32_bf16 v[130:133], v[178:181], v[202:205], v[130:133]
	v_mfma_f32_16x16x32_bf16 v[122:125], v[170:173], v[194:197], v[122:125]
	v_mfma_f32_16x16x32_bf16 v[114:117], v[178:181], v[194:197], v[114:117]
	s_waitcnt lgkmcnt(0)
	v_mfma_f32_16x16x32_bf16 v[106:109], v[170:173], v[186:189], v[106:109]
	v_mfma_f32_16x16x32_bf16 v[98:101], v[178:181], v[186:189], v[98:101]
	s_setprio 0
	s_setprio 1
	v_mfma_f32_16x16x32_bf16 v[134:137], v[150:153], v[206:209], v[134:137]
	v_mfma_f32_16x16x32_bf16 v[126:129], v[158:161], v[206:209], v[126:129]
	v_mfma_f32_16x16x32_bf16 v[118:121], v[150:153], v[198:201], v[118:121]
	v_mfma_f32_16x16x32_bf16 v[110:113], v[158:161], v[198:201], v[110:113]
	v_mfma_f32_16x16x32_bf16 v[102:105], v[150:153], v[190:193], v[102:105]
	v_mfma_f32_16x16x32_bf16 v[94:97], v[158:161], v[190:193], v[94:97]
	v_mfma_f32_16x16x32_bf16 v[90:93], v[150:153], v[182:185], v[90:93]
	v_mfma_f32_16x16x32_bf16 v[86:89], v[158:161], v[182:185], v[86:89]
	v_mfma_f32_16x16x32_bf16 v[134:137], v[154:157], v[210:213], v[134:137]
	v_mfma_f32_16x16x32_bf16 v[126:129], v[162:165], v[210:213], v[126:129]
	v_mfma_f32_16x16x32_bf16 v[118:121], v[154:157], v[202:205], v[118:121]
	v_mfma_f32_16x16x32_bf16 v[110:113], v[162:165], v[202:205], v[110:113]
	v_mfma_f32_16x16x32_bf16 v[102:105], v[154:157], v[194:197], v[102:105]
	v_mfma_f32_16x16x32_bf16 v[94:97], v[162:165], v[194:197], v[94:97]
	v_mfma_f32_16x16x32_bf16 v[90:93], v[154:157], v[186:189], v[90:93]
	v_mfma_f32_16x16x32_bf16 v[86:89], v[162:165], v[186:189], v[86:89]
	s_setprio 0
	v_cndmask_b32_e64 v4, 0, 1, s[78:79]
	s_and_b64 vcc, exec, s[42:43]
	v_cmp_ne_u32_e64 s[44:45], 1, v4
	s_cbranch_vccnz .LBB0_542
	s_and_b64 vcc, exec, s[44:45]
	s_mov_b64 s[20:21], -1
	s_cbranch_vccnz .LBB0_539
	v_mfma_f32_16x16x32_bf16 v[18:21], v[174:177], v[6:9], v[18:21]
	s_mov_b64 s[20:21], 0
	v_mfma_f32_16x16x32_bf16 v[14:17], v[158:161], v[6:9], v[14:17]
	v_mfma_f32_16x16x32_bf16 v[18:21], v[178:181], v[10:13], v[18:21]
	v_mfma_f32_16x16x32_bf16 v[14:17], v[162:165], v[10:13], v[14:17]

; #define PG8_STAGE(bufoff, gbase, voff) do { _Pragma("unroll") for (int _i = 0; _i < 2; ++_i) glds16_s((voff)[_i], (const void*)(gbase), ldsbase + (unsigned)((bufoff) + _i * 8192) + ldsw); } while (0)
; #define PG8_LDA(dst, b, h) do { _Pragma("unroll") for (int m = 0; m < 4; ++m) _Pragma("unroll") for (int k = 0; k < 2; ++k) dst[m][k] = *(const PG8_LAS bf16x8*)(lds + PG8_SA(b, h) + aoff + m * 2048 + k * 1024); } while (0)
; #define PG8_LDB(dst, b, h) do { _Pragma("unroll") for (int n = 0; n < 2; ++n) _Pragma("unroll") for (int k = 0; k < 2; ++k) dst[n][k] = *(const PG8_LAS bf16x8*)(lds + PG8_SB(b, h) + boff + n * 2048 + k * 1024); } while (0)
; #define PG8_LDX(pb, tp) do { _Pragma("unroll") for (int k = 0; k < 2; ++k) Ax[k] = *(const PG8_LAS bf16x8*)(lds + xoff + (pb) * 4096 + (tp) * 128 + k * 64); } while (0)
; #define PG8_MMA(ai, bj, At, Bt) do { __builtin_amdgcn_s_setprio(1); _Pragma("unroll") for (int m = 0; m < 4; ++m) _Pragma("unroll") for (int n = 0; n < 2; ++n) _Pragma("unroll") for (int k = 0; k < 2; ++k) \
;         acc[ai][bj][m][n] = __builtin_amdgcn_mfma_f32_16x16x32_bf16(Bt[n][k], At[m][k], acc[ai][bj][m][n], 0, 0, 0); __builtin_amdgcn_s_setprio(0); } while (0)
; #define PG8_WAIT_V(n) asm volatile("s_waitcnt vmcnt(" #n ")" ::: "memory")
; #define PG8_WAIT_L(n) asm volatile("s_waitcnt lgkmcnt(" #n ")" ::: "memory")
; #define PG8_BAR __builtin_amdgcn_s_barrier()
; #define PG8_SCHED __builtin_amdgcn_sched_barrier(0)
; template <class Epi, class Sched, bool HM = false>
; __device__ __forceinline__ void gemm_phase(PG8_LAS unsigned char* lds, const Gemm g, const Sched& S, const Epi& E) {
;     ...
;             if (!HM) PG8_LDA(At, 0, 1); PG8_STAGE(PG8_SB(0, 0), b2, voffB); PG8_STAGE(PG8_SB(0, 1), b2 + hstepB, voffB); PG8_STAGE(PG8_SA(0, 0), a2, voffA);
;             PG8_WAIT_V(9); PG8_WAIT_L(0); PG8_BAR; if (!HM) { PG8_MMA(1, 0, At, B0); PG8_MMA(1, 1, At, B1); } PG8_BAR; PG8_SCHED;
;             PG8_LDB(B0, 1, 0); PG8_LDB(B1, 1, 1); PG8_SCHED; PG8_LDA(At, 1, 0); if (hasx) PG8_LDX(pb, 1); PG8_STAGE(PG8_SA(0, 1), a2 + hstepA, voffA);
.LBB0_541:
.LBB0_542:
	s_barrier
	ds_read_b128 v[182:185], v235 offset:16384
	ds_read_b128 v[186:189], v235 offset:17408
	ds_read_b128 v[190:193], v235 offset:18432
	ds_read_b128 v[194:197], v235 offset:19456
	ds_read_b128 v[198:201], v235 offset:20480
	ds_read_b128 v[202:205], v235 offset:21504
	ds_read_b128 v[206:209], v235 offset:22528
	ds_read_b128 v[210:213], v235 offset:23552
	s_mov_b32 s20, m0
	s_mov_b32 m0, s19
	s_nop 0
	global_load_lds_dwordx4 v226, s[8:9]
	s_mov_b32 m0, s20
	s_nop 0
	s_mov_b32 s20, m0
	s_mov_b32 m0, s24
	s_nop 0
	global_load_lds_dwordx4 v228, s[8:9]
	s_mov_b32 m0, s20
	s_add_u32 s8, s8, 0x80000
	s_addc_u32 s9, s9, 0
	s_mov_b32 s20, m0
	s_mov_b32 m0, s25
	s_nop 0
	global_load_lds_dwordx4 v226, s[8:9]
	s_mov_b32 m0, s20
	s_nop 0
	s_mov_b32 s20, m0
	s_mov_b32 m0, s28
	s_nop 0
	global_load_lds_dwordx4 v228, s[8:9]
	s_mov_b32 m0, s20
	s_mov_b32 s8, m0
	s_mov_b32 m0, s18
	s_nop 0
	global_load_lds_dwordx4 v225, s[94:95]
	s_mov_b32 m0, s8
	s_nop 0
	s_mov_b32 s8, m0
	s_mov_b32 m0, s29
	s_nop 0
	global_load_lds_dwordx4 v227, s[94:95]
	s_mov_b32 m0, s8
	s_waitcnt vmcnt(9)
	s_waitcnt lgkmcnt(0)
	s_barrier
	s_setprio 1
	s_waitcnt lgkmcnt(7)
	v_mfma_f32_16x16x32_bf16 v[82:85], v[166:169], v[182:185], v[82:85]
	v_mfma_f32_16x16x32_bf16 v[78:81], v[174:177], v[182:185], v[78:81]
	s_waitcnt lgkmcnt(5)
	v_mfma_f32_16x16x32_bf16 v[74:77], v[166:169], v[190:193], v[74:77]
	v_mfma_f32_16x16x32_bf16 v[66:69], v[174:177], v[190:193], v[66:69]
	s_waitcnt lgkmcnt(3)
	v_mfma_f32_16x16x32_bf16 v[58:61], v[166:169], v[198:201], v[58:61]
	v_mfma_f32_16x16x32_bf16 v[50:53], v[174:177], v[198:201], v[50:53]
	s_waitcnt lgkmcnt(1)
	v_mfma_f32_16x16x32_bf16 v[42:45], v[166:169], v[206:209], v[42:45]
	v_mfma_f32_16x16x32_bf16 v[34:37], v[174:177], v[206:209], v[34:37]
	v_mfma_f32_16x16x32_bf16 v[82:85], v[170:173], v[186:189], v[82:85]
	v_mfma_f32_16x16x32_bf16 v[78:81], v[178:181], v[186:189], v[78:81]
	v_mfma_f32_16x16x32_bf16 v[74:77], v[170:173], v[194:197], v[74:77]
	v_mfma_f32_16x16x32_bf16 v[66:69], v[178:181], v[194:197], v[66:69]
	v_mfma_f32_16x16x32_bf16 v[58:61], v[170:173], v[202:205], v[58:61]
	v_mfma_f32_16x16x32_bf16 v[50:53], v[178:181], v[202:205], v[50:53]
	s_waitcnt lgkmcnt(0)
	v_mfma_f32_16x16x32_bf16 v[42:45], v[170:173], v[210:213], v[42:45]
	v_mfma_f32_16x16x32_bf16 v[34:37], v[178:181], v[210:213], v[34:37]
	s_setprio 0
	s_setprio 1
	v_mfma_f32_16x16x32_bf16 v[70:73], v[150:153], v[182:185], v[70:73]
	v_mfma_f32_16x16x32_bf16 v[62:65], v[158:161], v[182:185], v[62:65]
	v_mfma_f32_16x16x32_bf16 v[54:57], v[150:153], v[190:193], v[54:57]
	v_mfma_f32_16x16x32_bf16 v[46:49], v[158:161], v[190:193], v[46:49]
	v_mfma_f32_16x16x32_bf16 v[38:41], v[150:153], v[198:201], v[38:41]
	v_mfma_f32_16x16x32_bf16 v[30:33], v[158:161], v[198:201], v[30:33]
	v_mfma_f32_16x16x32_bf16 v[26:29], v[150:153], v[206:209], v[26:29]
	v_mfma_f32_16x16x32_bf16 v[22:25], v[158:161], v[206:209], v[22:25]
	v_mfma_f32_16x16x32_bf16 v[70:73], v[154:157], v[186:189], v[70:73]
	v_mfma_f32_16x16x32_bf16 v[62:65], v[162:165], v[186:189], v[62:65]
	v_mfma_f32_16x16x32_bf16 v[54:57], v[154:157], v[194:197], v[54:57]
	v_mfma_f32_16x16x32_bf16 v[46:49], v[162:165], v[194:197], v[46:49]
	v_mfma_f32_16x16x32_bf16 v[38:41], v[154:157], v[202:205], v[38:41]
	v_mfma_f32_16x16x32_bf16 v[30:33], v[162:165], v[202:205], v[30:33]
	v_mfma_f32_16x16x32_bf16 v[26:29], v[154:157], v[210:213], v[26:29]
	v_mfma_f32_16x16x32_bf16 v[22:25], v[162:165], v[210:213], v[22:25]
	s_setprio 0
	s_barrier
	v_add_u32_e32 v4, 0x18000, v234
	ds_read_b128 v[166:169], v4
	ds_read_b128 v[170:173], v4 offset:1024
	ds_read_b128 v[174:177], v4 offset:2048
	ds_read_b128 v[178:181], v4 offset:3072
	v_add_u32_e32 v4, 0x1c000, v234
	ds_read_b128 v[150:153], v4
	ds_read_b128 v[154:157], v4 offset:1024
	ds_read_b128 v[158:161], v4 offset:2048
	ds_read_b128 v[162:165], v4 offset:3072
	ds_read_b128 v[206:209], v235 offset:32768
	ds_read_b128 v[210:213], v235 offset:33792
	ds_read_b128 v[198:201], v235 offset:34816
	ds_read_b128 v[202:205], v235 offset:35840
	ds_read_b128 v[190:193], v235 offset:36864
	ds_read_b128 v[194:197], v235 offset:37888
	ds_read_b128 v[182:185], v235 offset:38912
	ds_read_b128 v[186:189], v235 offset:39936
	s_and_b64 vcc, exec, s[42:43]
	s_cbranch_vccnz .LBB0_544
	ds_read_b128 v[6:9], v2 offset:128
	ds_read_b128 v[10:13], v2 offset:192
; #define PG8_STAGE(bufoff, gbase, voff) do { _Pragma("unroll") for (int _i = 0; _i < 2; ++_i) glds16_s((voff)[_i], (const void*)(gbase), ldsbase + (unsigned)((bufoff) + _i * 8192) + ldsw); } while (0)
; #define PG8_LDA(dst, b, h) do { _Pragma("unroll") for (int m = 0; m < 4; ++m) _Pragma("unroll") for (int k = 0; k < 2; ++k) dst[m][k] = *(const PG8_LAS bf16x8*)(lds + PG8_SA(b, h) + aoff + m * 2048 + k * 1024); } while (0)
; #define PG8_LDB(dst, b, h) do { _Pragma("unroll") for (int n = 0; n < 2; ++n) _Pragma("unroll") for (int k = 0; k < 2; ++k) dst[n][k] = *(const PG8_LAS bf16x8*)(lds + PG8_SB(b, h) + boff + n * 2048 + k * 1024); } while (0)
; #define PG8_LDX(pb, tp) do { _Pragma("unroll") for (int k = 0; k < 2; ++k) Ax[k] = *(const PG8_LAS bf16x8*)(lds + xoff + (pb) * 4096 + (tp) * 128 + k * 64); } while (0)
; #define PG8_MMA(ai, bj, At, Bt) do { __builtin_amdgcn_s_setprio(1); _Pragma("unroll") for (int m = 0; m < 4; ++m) _Pragma("unroll") for (int n = 0; n < 2; ++n) _Pragma("unroll") for (int k = 0; k < 2; ++k) \
;         acc[ai][bj][m][n] = __builtin_amdgcn_mfma_f32_16x16x32_bf16(Bt[n][k], At[m][k], acc[ai][bj][m][n], 0, 0, 0); __builtin_amdgcn_s_setprio(0); } while (0)
; #define PG8_WAIT_V(n) asm volatile("s_waitcnt vmcnt(" #n ")" ::: "memory")
; #define PG8_WAIT_L(n) asm volatile("s_waitcnt lgkmcnt(" #n ")" ::: "memory")
; #define PG8_BAR __builtin_amdgcn_s_barrier()
; #define PG8_SCHED __builtin_amdgcn_sched_barrier(0)
; template <class Epi, class Sched, bool HM = false>
; __device__ __forceinline__ void gemm_phase(PG8_LAS unsigned char* lds, const Gemm g, const Sched& S, const Epi& E) {
;     ...
;             PG8_LDB(B0, 1, 0); PG8_LDB(B1, 1, 1); PG8_SCHED; PG8_LDA(At, 1, 0); if (hasx) PG8_LDX(pb, 1); PG8_STAGE(PG8_SA(0, 1), a2 + hstepA, voffA);
;             PG8_WAIT_V(9); PG8_WAIT_L(0); PG8_BAR; PG8_MMA(0, 0, At, B0); PG8_MMA(0, 1, At, B1); if (hasx) PG8_MMAX(); PG8_BAR; PG8_SCHED;
.LBB0_544:
	s_add_u32 s8, s94, 0x80000
	s_addc_u32 s9, s95, 0
	s_mov_b32 s20, m0
	s_mov_b32 m0, s31
	s_nop 0
	global_load_lds_dwordx4 v225, s[8:9]
	s_mov_b32 m0, s20
	s_nop 0
	s_mov_b32 s20, m0
	s_mov_b32 m0, s36
	s_nop 0
	global_load_lds_dwordx4 v227, s[8:9]
	s_mov_b32 m0, s20
	s_waitcnt vmcnt(9)
	s_waitcnt lgkmcnt(0)
	s_barrier
	s_setprio 1
	s_waitcnt lgkmcnt(7)
	v_mfma_f32_16x16x32_bf16 v[146:149], v[166:169], v[206:209], v[146:149]
	v_mfma_f32_16x16x32_bf16 v[142:145], v[174:177], v[206:209], v[142:145]
	s_waitcnt lgkmcnt(5)
	v_mfma_f32_16x16x32_bf16 v[138:141], v[166:169], v[198:201], v[138:141]
	v_mfma_f32_16x16x32_bf16 v[130:133], v[174:177], v[198:201], v[130:133]
	s_waitcnt lgkmcnt(3)
	v_mfma_f32_16x16x32_bf16 v[122:125], v[166:169], v[190:193], v[122:125]
	v_mfma_f32_16x16x32_bf16 v[114:117], v[174:177], v[190:193], v[114:117]
	s_waitcnt lgkmcnt(1)
	v_mfma_f32_16x16x32_bf16 v[106:109], v[166:169], v[182:185], v[106:109]
	v_mfma_f32_16x16x32_bf16 v[98:101], v[174:177], v[182:185], v[98:101]
	v_mfma_f32_16x16x32_bf16 v[146:149], v[170:173], v[210:213], v[146:149]
	v_mfma_f32_16x16x32_bf16 v[142:145], v[178:181], v[210:213], v[142:145]
	v_mfma_f32_16x16x32_bf16 v[138:141], v[170:173], v[202:205], v[138:141]
	v_mfma_f32_16x16x32_bf16 v[130:133], v[178:181], v[202:205], v[130:133]
	v_mfma_f32_16x16x32_bf16 v[122:125], v[170:173], v[194:197], v[122:125]
	v_mfma_f32_16x16x32_bf16 v[114:117], v[178:181], v[194:197], v[114:117]
	s_waitcnt lgkmcnt(0)
	v_mfma_f32_16x16x32_bf16 v[106:109], v[170:173], v[186:189], v[106:109]
	v_mfma_f32_16x16x32_bf16 v[98:101], v[178:181], v[186:189], v[98:101]
	s_setprio 0
	s_setprio 1
	v_mfma_f32_16x16x32_bf16 v[134:137], v[150:153], v[206:209], v[134:137]
	v_mfma_f32_16x16x32_bf16 v[126:129], v[158:161], v[206:209], v[126:129]
	v_mfma_f32_16x16x32_bf16 v[118:121], v[150:153], v[198:201], v[118:121]
	v_mfma_f32_16x16x32_bf16 v[110:113], v[158:161], v[198:201], v[110:113]
	v_mfma_f32_16x16x32_bf16 v[102:105], v[150:153], v[190:193], v[102:105]
	v_mfma_f32_16x16x32_bf16 v[94:97], v[158:161], v[190:193], v[94:97]
	v_mfma_f32_16x16x32_bf16 v[90:93], v[150:153], v[182:185], v[90:93]
	v_mfma_f32_16x16x32_bf16 v[86:89], v[158:161], v[182:185], v[86:89]
	v_mfma_f32_16x16x32_bf16 v[134:137], v[154:157], v[210:213], v[134:137]
	v_mfma_f32_16x16x32_bf16 v[126:129], v[162:165], v[210:213], v[126:129]
	v_mfma_f32_16x16x32_bf16 v[118:121], v[154:157], v[202:205], v[118:121]
	v_mfma_f32_16x16x32_bf16 v[110:113], v[162:165], v[202:205], v[110:113]
	v_mfma_f32_16x16x32_bf16 v[102:105], v[154:157], v[194:197], v[102:105]
	v_mfma_f32_16x16x32_bf16 v[94:97], v[162:165], v[194:197], v[94:97]
	v_mfma_f32_16x16x32_bf16 v[90:93], v[154:157], v[186:189], v[90:93]
	v_mfma_f32_16x16x32_bf16 v[86:89], v[162:165], v[186:189], v[86:89]
	s_setprio 0
	s_and_b64 vcc, exec, s[42:43]
	s_cbranch_vccnz .LBB0_533
	s_and_b64 vcc, exec, s[44:45]
	s_mov_b64 s[8:9], -1
	s_cbranch_vccnz .LBB0_547
	v_mfma_f32_16x16x32_bf16 v[18:21], v[174:177], v[6:9], v[18:21]
	s_mov_b64 s[8:9], 0
	v_mfma_f32_16x16x32_bf16 v[14:17], v[158:161], v[6:9], v[14:17]
	v_mfma_f32_16x16x32_bf16 v[18:21], v[178:181], v[10:13], v[18:21]
	v_mfma_f32_16x16x32_bf16 v[14:17], v[162:165], v[10:13], v[14:17]

; #define PG8_STAGE(bufoff, gbase, voff) do { _Pragma("unroll") for (int _i = 0; _i < 2; ++_i) glds16_s((voff)[_i], (const void*)(gbase), ldsbase + (unsigned)((bufoff) + _i * 8192) + ldsw); } while (0)
; #define PG8_LDA(dst, b, h) do { _Pragma("unroll") for (int m = 0; m < 4; ++m) _Pragma("unroll") for (int k = 0; k < 2; ++k) dst[m][k] = *(const PG8_LAS bf16x8*)(lds + PG8_SA(b, h) + aoff + m * 2048 + k * 1024); } while (0)
; #define PG8_MMA(ai, bj, At, Bt) do { __builtin_amdgcn_s_setprio(1); _Pragma("unroll") for (int m = 0; m < 4; ++m) _Pragma("unroll") for (int n = 0; n < 2; ++n) _Pragma("unroll") for (int k = 0; k < 2; ++k) \
;         acc[ai][bj][m][n] = __builtin_amdgcn_mfma_f32_16x16x32_bf16(Bt[n][k], At[m][k], acc[ai][bj][m][n], 0, 0, 0); __builtin_amdgcn_s_setprio(0); } while (0)
; #define PG8_WAIT_V(n) asm volatile("s_waitcnt vmcnt(" #n ")" ::: "memory")
; #define PG8_WAIT_L(n) asm volatile("s_waitcnt lgkmcnt(" #n ")" ::: "memory")
; #define PG8_BAR __builtin_amdgcn_s_barrier()
; #define PG8_SCHED __builtin_amdgcn_sched_barrier(0)
; template <class Epi, class Sched, bool HM = false>
; __device__ __forceinline__ void gemm_phase(PG8_LAS unsigned char* lds, const Gemm g, const Sched& S, const Epi& E) {
;     ...
;             if (!HM) PG8_LDA(At, 1, 1); PG8_STAGE(PG8_SB(1, 0), b3, voffB); PG8_STAGE(PG8_SB(1, 1), b3 + hstepB, voffB); PG8_STAGE(PG8_SA(1, 0), a3, voffA);
;             PG8_WAIT_V(8); PG8_WAIT_L(0); PG8_BAR; if (!HM) { PG8_MMA(1, 0, At, B0); PG8_MMA(1, 1, At, B1); } PG8_BAR; PG8_SCHED;
;         }
.LBB0_579:
.LBB0_580:
	s_barrier
	ds_read_b128 v[182:185], v235 offset:49152
	ds_read_b128 v[186:189], v235 offset:50176
	ds_read_b128 v[190:193], v235 offset:51200
	ds_read_b128 v[194:197], v235 offset:52224
	ds_read_b128 v[198:201], v235 offset:53248
	ds_read_b128 v[202:205], v235 offset:54272
	ds_read_b128 v[206:209], v235 offset:55296
	ds_read_b128 v[210:213], v235 offset:56320
	s_mov_b32 s8, m0
	s_mov_b32 m0, s29
	s_nop 0
	global_load_lds_dwordx4 v226, s[6:7]
	s_mov_b32 m0, s8
	s_nop 0
	s_mov_b32 s8, m0
	s_mov_b32 m0, s30
	s_nop 0
	global_load_lds_dwordx4 v228, s[6:7]
	s_mov_b32 m0, s8
	s_add_u32 s6, s6, 0x80000
	s_addc_u32 s7, s7, 0
	s_mov_b32 s8, m0
	s_mov_b32 m0, s25
	s_nop 0
	global_load_lds_dwordx4 v226, s[6:7]
	s_mov_b32 m0, s8
	s_nop 0
	s_mov_b32 s8, m0
	s_mov_b32 m0, s12
	s_nop 0
	global_load_lds_dwordx4 v228, s[6:7]
	s_mov_b32 m0, s8
	s_mov_b32 s6, m0
	s_mov_b32 m0, s31
	s_nop 0
	global_load_lds_dwordx4 v225, s[4:5]
	s_mov_b32 m0, s6
	s_nop 0
	s_mov_b32 s6, m0
	s_mov_b32 m0, s24
	s_nop 0
	global_load_lds_dwordx4 v227, s[4:5]
	s_mov_b32 m0, s6
	s_waitcnt vmcnt(8)
	s_waitcnt lgkmcnt(0)
	s_barrier
	s_setprio 1
	s_waitcnt lgkmcnt(7)
	v_mfma_f32_16x16x32_bf16 v[82:85], v[166:169], v[182:185], v[82:85]
	v_mfma_f32_16x16x32_bf16 v[78:81], v[174:177], v[182:185], v[78:81]
	s_waitcnt lgkmcnt(5)
	v_mfma_f32_16x16x32_bf16 v[66:69], v[166:169], v[190:193], v[66:69]
	v_mfma_f32_16x16x32_bf16 v[62:65], v[174:177], v[190:193], v[62:65]
	s_waitcnt lgkmcnt(3)
	v_mfma_f32_16x16x32_bf16 v[50:53], v[166:169], v[198:201], v[50:53]
	v_mfma_f32_16x16x32_bf16 v[46:49], v[174:177], v[198:201], v[46:49]
	s_waitcnt lgkmcnt(1)
	v_mfma_f32_16x16x32_bf16 v[34:37], v[166:169], v[206:209], v[34:37]
	v_mfma_f32_16x16x32_bf16 v[30:33], v[174:177], v[206:209], v[30:33]
	v_mfma_f32_16x16x32_bf16 v[82:85], v[170:173], v[186:189], v[82:85]
	v_mfma_f32_16x16x32_bf16 v[78:81], v[178:181], v[186:189], v[78:81]
	v_mfma_f32_16x16x32_bf16 v[66:69], v[170:173], v[194:197], v[66:69]
	v_mfma_f32_16x16x32_bf16 v[62:65], v[178:181], v[194:197], v[62:65]
	v_mfma_f32_16x16x32_bf16 v[50:53], v[170:173], v[202:205], v[50:53]
	v_mfma_f32_16x16x32_bf16 v[46:49], v[178:181], v[202:205], v[46:49]
	s_waitcnt lgkmcnt(0)
	v_mfma_f32_16x16x32_bf16 v[34:37], v[170:173], v[210:213], v[34:37]
	v_mfma_f32_16x16x32_bf16 v[30:33], v[178:181], v[210:213], v[30:33]
	s_setprio 0
	s_setprio 1
	v_mfma_f32_16x16x32_bf16 v[74:77], v[150:153], v[182:185], v[74:77]
	v_mfma_f32_16x16x32_bf16 v[70:73], v[158:161], v[182:185], v[70:73]
	v_mfma_f32_16x16x32_bf16 v[58:61], v[150:153], v[190:193], v[58:61]
	v_mfma_f32_16x16x32_bf16 v[54:57], v[158:161], v[190:193], v[54:57]
	v_mfma_f32_16x16x32_bf16 v[42:45], v[150:153], v[198:201], v[42:45]
	v_mfma_f32_16x16x32_bf16 v[38:41], v[158:161], v[198:201], v[38:41]
	v_mfma_f32_16x16x32_bf16 v[26:29], v[150:153], v[206:209], v[26:29]
	v_mfma_f32_16x16x32_bf16 v[22:25], v[158:161], v[206:209], v[22:25]
	v_mfma_f32_16x16x32_bf16 v[74:77], v[154:157], v[186:189], v[74:77]
	v_mfma_f32_16x16x32_bf16 v[70:73], v[162:165], v[186:189], v[70:73]
	v_mfma_f32_16x16x32_bf16 v[58:61], v[154:157], v[194:197], v[58:61]
	v_mfma_f32_16x16x32_bf16 v[54:57], v[162:165], v[194:197], v[54:57]
	v_mfma_f32_16x16x32_bf16 v[42:45], v[154:157], v[202:205], v[42:45]
	v_mfma_f32_16x16x32_bf16 v[38:41], v[162:165], v[202:205], v[38:41]
	v_mfma_f32_16x16x32_bf16 v[26:29], v[154:157], v[210:213], v[26:29]
	v_mfma_f32_16x16x32_bf16 v[22:25], v[162:165], v[210:213], v[22:25]
	s_setprio 0
	s_barrier
	s_add_i32 s23, s23, 2
	s_addk_i32 s22, 0x1000
	s_add_u32 s61, s61, 0x100
	s_addc_u32 s44, s44, 0
	s_add_u32 s82, s82, 0x100
	s_addc_u32 s27, s27, 0
	s_cmp_gt_u32 s23, 29
	s_cbranch_scc1 .LBB0_596

; #define PG8_STAGE(bufoff, gbase, voff) do { _Pragma("unroll") for (int _i = 0; _i < 2; ++_i) glds16_s((voff)[_i], (const void*)(gbase), ldsbase + (unsigned)((bufoff) + _i * 8192) + ldsw); } while (0)
; #define PG8_STAGEX(pb, gbase) glds16_s(voffX, (const void*)(gbase), ldsbase + (unsigned)(XOFF + (pb) * 4096) + ldsx)
; #define PG8_LDA(dst, b, h) do { _Pragma("unroll") for (int m = 0; m < 4; ++m) _Pragma("unroll") for (int k = 0; k < 2; ++k) dst[m][k] = *(const PG8_LAS bf16x8*)(lds + PG8_SA(b, h) + aoff + m * 2048 + k * 1024); } while (0)
; #define PG8_LDB(dst, b, h) do { _Pragma("unroll") for (int n = 0; n < 2; ++n) _Pragma("unroll") for (int k = 0; k < 2; ++k) dst[n][k] = *(const PG8_LAS bf16x8*)(lds + PG8_SB(b, h) + boff + n * 2048 + k * 1024); } while (0)
; #define PG8_LDX(pb, tp) do { _Pragma("unroll") for (int k = 0; k < 2; ++k) Ax[k] = *(const PG8_LAS bf16x8*)(lds + xoff + (pb) * 4096 + (tp) * 128 + k * 64); } while (0)
; #define PG8_MMA(ai, bj, At, Bt) do { __builtin_amdgcn_s_setprio(1); _Pragma("unroll") for (int m = 0; m < 4; ++m) _Pragma("unroll") for (int n = 0; n < 2; ++n) _Pragma("unroll") for (int k = 0; k < 2; ++k) \
;         acc[ai][bj][m][n] = __builtin_amdgcn_mfma_f32_16x16x32_bf16(Bt[n][k], At[m][k], acc[ai][bj][m][n], 0, 0, 0); __builtin_amdgcn_s_setprio(0); } while (0)
; #define PG8_WAIT_V(n) asm volatile("s_waitcnt vmcnt(" #n ")" ::: "memory")
; #define PG8_WAIT_L(n) asm volatile("s_waitcnt lgkmcnt(" #n ")" ::: "memory")
; #define PG8_BAR __builtin_amdgcn_s_barrier()
; #define PG8_SCHED __builtin_amdgcn_sched_barrier(0)
; template <class Epi, class Sched, bool HM = false>
; __device__ __forceinline__ void gemm_phase(PG8_LAS unsigned char* lds, const Gemm g, const Sched& S, const Epi& E) {
;     ...
;             PG8_LDB(B0, 0, 0); PG8_LDB(B1, 0, 1); PG8_SCHED; PG8_LDA(At, 0, 0); if (hasx) PG8_LDX(pb, 0); PG8_STAGE(PG8_SA(1, 1), a1 + hstepA, voffA); PG8_STAGEX(pb ^ 1, a2 + xstep);
;             PG8_WAIT_V(9); PG8_WAIT_L(0); PG8_BAR; PG8_MMA(0, 0, At, B0); PG8_MMA(0, 1, At, B1); if (hasx) PG8_MMAX(); PG8_BAR; PG8_SCHED;
.LBB0_583:
	s_add_u32 s42, s42, 0x80000
	s_addc_u32 s43, s43, 0
	s_mov_b32 s21, m0
	s_mov_b32 m0, s13
	s_nop 0
	global_load_lds_dwordx4 v225, s[42:43]
	s_mov_b32 m0, s21
	s_nop 0
	s_mov_b32 s21, m0
	s_mov_b32 m0, s52
	s_nop 0
	global_load_lds_dwordx4 v227, s[42:43]
	s_mov_b32 m0, s21
	s_add_u32 s42, s8, 0x100000
	s_addc_u32 s43, s9, 0
	s_xor_b32 s20, s20, 0x21400
	s_add_i32 s20, s18, s20
	s_mov_b32 s21, m0
	s_mov_b32 m0, s20
	s_nop 0
	global_load_lds_dwordx4 v229, s[42:43]
	s_mov_b32 m0, s21
	s_waitcnt vmcnt(9)
	s_waitcnt lgkmcnt(0)
	s_barrier
	s_setprio 1
	s_waitcnt lgkmcnt(7)
	v_mfma_f32_16x16x32_bf16 v[146:149], v[166:169], v[206:209], v[146:149]
	v_mfma_f32_16x16x32_bf16 v[142:145], v[174:177], v[206:209], v[142:145]
	s_waitcnt lgkmcnt(5)
	v_mfma_f32_16x16x32_bf16 v[130:133], v[166:169], v[198:201], v[130:133]
	v_mfma_f32_16x16x32_bf16 v[126:129], v[174:177], v[198:201], v[126:129]
	s_waitcnt lgkmcnt(3)
	v_mfma_f32_16x16x32_bf16 v[114:117], v[166:169], v[190:193], v[114:117]
	v_mfma_f32_16x16x32_bf16 v[110:113], v[174:177], v[190:193], v[110:113]
	s_waitcnt lgkmcnt(1)
	v_mfma_f32_16x16x32_bf16 v[98:101], v[166:169], v[182:185], v[98:101]
	v_mfma_f32_16x16x32_bf16 v[94:97], v[174:177], v[182:185], v[94:97]
	v_mfma_f32_16x16x32_bf16 v[146:149], v[170:173], v[210:213], v[146:149]
	v_mfma_f32_16x16x32_bf16 v[142:145], v[178:181], v[210:213], v[142:145]
	v_mfma_f32_16x16x32_bf16 v[130:133], v[170:173], v[202:205], v[130:133]
	v_mfma_f32_16x16x32_bf16 v[126:129], v[178:181], v[202:205], v[126:129]
	v_mfma_f32_16x16x32_bf16 v[114:117], v[170:173], v[194:197], v[114:117]
	v_mfma_f32_16x16x32_bf16 v[110:113], v[178:181], v[194:197], v[110:113]
	s_waitcnt lgkmcnt(0)
	v_mfma_f32_16x16x32_bf16 v[98:101], v[170:173], v[186:189], v[98:101]
	v_mfma_f32_16x16x32_bf16 v[94:97], v[178:181], v[186:189], v[94:97]
	s_setprio 0
	s_setprio 1
	v_mfma_f32_16x16x32_bf16 v[138:141], v[150:153], v[206:209], v[138:141]
	v_mfma_f32_16x16x32_bf16 v[134:137], v[158:161], v[206:209], v[134:137]
	v_mfma_f32_16x16x32_bf16 v[122:125], v[150:153], v[198:201], v[122:125]
	v_mfma_f32_16x16x32_bf16 v[118:121], v[158:161], v[198:201], v[118:121]
	v_mfma_f32_16x16x32_bf16 v[106:109], v[150:153], v[190:193], v[106:109]
	v_mfma_f32_16x16x32_bf16 v[102:105], v[158:161], v[190:193], v[102:105]
	v_mfma_f32_16x16x32_bf16 v[90:93], v[150:153], v[182:185], v[90:93]
	v_mfma_f32_16x16x32_bf16 v[86:89], v[158:161], v[182:185], v[86:89]
	v_mfma_f32_16x16x32_bf16 v[138:141], v[154:157], v[210:213], v[138:141]
	v_mfma_f32_16x16x32_bf16 v[134:137], v[162:165], v[210:213], v[134:137]
	v_mfma_f32_16x16x32_bf16 v[122:125], v[154:157], v[202:205], v[122:125]
	v_mfma_f32_16x16x32_bf16 v[118:121], v[162:165], v[202:205], v[118:121]
	v_mfma_f32_16x16x32_bf16 v[106:109], v[154:157], v[194:197], v[106:109]
	v_mfma_f32_16x16x32_bf16 v[102:105], v[162:165], v[194:197], v[102:105]
	v_mfma_f32_16x16x32_bf16 v[90:93], v[154:157], v[186:189], v[90:93]
	v_mfma_f32_16x16x32_bf16 v[86:89], v[162:165], v[186:189], v[86:89]
	s_setprio 0
	v_cndmask_b32_e64 v4, 0, 1, s[96:97]
	s_and_b64 vcc, exec, s[40:41]
	v_cmp_ne_u32_e64 s[42:43], 1, v4
	s_cbranch_vccnz .LBB0_589
	s_and_b64 vcc, exec, s[42:43]
	s_mov_b64 s[20:21], -1
	s_cbranch_vccnz .LBB0_586
	v_mfma_f32_16x16x32_bf16 v[18:21], v[174:177], v[6:9], v[18:21]
	s_mov_b64 s[20:21], 0
	v_mfma_f32_16x16x32_bf16 v[14:17], v[158:161], v[6:9], v[14:17]
	v_mfma_f32_16x16x32_bf16 v[18:21], v[178:181], v[10:13], v[18:21]
	v_mfma_f32_16x16x32_bf16 v[14:17], v[162:165], v[10:13], v[14:17]

; #define PG8_STAGE(bufoff, gbase, voff) do { _Pragma("unroll") for (int _i = 0; _i < 2; ++_i) glds16_s((voff)[_i], (const void*)(gbase), ldsbase + (unsigned)((bufoff) + _i * 8192) + ldsw); } while (0)
; #define PG8_LDA(dst, b, h) do { _Pragma("unroll") for (int m = 0; m < 4; ++m) _Pragma("unroll") for (int k = 0; k < 2; ++k) dst[m][k] = *(const PG8_LAS bf16x8*)(lds + PG8_SA(b, h) + aoff + m * 2048 + k * 1024); } while (0)
; #define PG8_LDB(dst, b, h) do { _Pragma("unroll") for (int n = 0; n < 2; ++n) _Pragma("unroll") for (int k = 0; k < 2; ++k) dst[n][k] = *(const PG8_LAS bf16x8*)(lds + PG8_SB(b, h) + boff + n * 2048 + k * 1024); } while (0)
; #define PG8_LDX(pb, tp) do { _Pragma("unroll") for (int k = 0; k < 2; ++k) Ax[k] = *(const PG8_LAS bf16x8*)(lds + xoff + (pb) * 4096 + (tp) * 128 + k * 64); } while (0)
; #define PG8_MMA(ai, bj, At, Bt) do { __builtin_amdgcn_s_setprio(1); _Pragma("unroll") for (int m = 0; m < 4; ++m) _Pragma("unroll") for (int n = 0; n < 2; ++n) _Pragma("unroll") for (int k = 0; k < 2; ++k) \
;         acc[ai][bj][m][n] = __builtin_amdgcn_mfma_f32_16x16x32_bf16(Bt[n][k], At[m][k], acc[ai][bj][m][n], 0, 0, 0); __builtin_amdgcn_s_setprio(0); } while (0)
; #define PG8_WAIT_V(n) asm volatile("s_waitcnt vmcnt(" #n ")" ::: "memory")
; #define PG8_WAIT_L(n) asm volatile("s_waitcnt lgkmcnt(" #n ")" ::: "memory")
; #define PG8_BAR __builtin_amdgcn_s_barrier()
; #define PG8_SCHED __builtin_amdgcn_sched_barrier(0)
; template <class Epi, class Sched, bool HM = false>
; __device__ __forceinline__ void gemm_phase(PG8_LAS unsigned char* lds, const Gemm g, const Sched& S, const Epi& E) {
;     ...
;             if (!HM) PG8_LDA(At, 0, 1); PG8_STAGE(PG8_SB(0, 0), b2, voffB); PG8_STAGE(PG8_SB(0, 1), b2 + hstepB, voffB); PG8_STAGE(PG8_SA(0, 0), a2, voffA);
;             PG8_WAIT_V(9); PG8_WAIT_L(0); PG8_BAR; if (!HM) { PG8_MMA(1, 0, At, B0); PG8_MMA(1, 1, At, B1); } PG8_BAR; PG8_SCHED;
;             PG8_LDB(B0, 1, 0); PG8_LDB(B1, 1, 1); PG8_SCHED; PG8_LDA(At, 1, 0); if (hasx) PG8_LDX(pb, 1); PG8_STAGE(PG8_SA(0, 1), a2 + hstepA, voffA);
.LBB0_588:
.LBB0_589:
	s_barrier
	ds_read_b128 v[182:185], v235 offset:16384
	ds_read_b128 v[186:189], v235 offset:17408
	ds_read_b128 v[190:193], v235 offset:18432
	ds_read_b128 v[194:197], v235 offset:19456
	ds_read_b128 v[198:201], v235 offset:20480
	ds_read_b128 v[202:205], v235 offset:21504
	ds_read_b128 v[206:209], v235 offset:22528
	ds_read_b128 v[210:213], v235 offset:23552
	s_mov_b32 s20, m0
	s_mov_b32 m0, s83
	s_nop 0
	global_load_lds_dwordx4 v226, s[34:35]
	s_mov_b32 m0, s20
	s_nop 0
	s_mov_b32 s20, m0
	s_mov_b32 m0, s36
	s_nop 0
	global_load_lds_dwordx4 v228, s[34:35]
	s_mov_b32 m0, s20
	s_add_u32 s20, s34, 0x80000
	s_addc_u32 s21, s35, 0
	s_mov_b32 s34, m0
	s_mov_b32 m0, s37
	s_nop 0
	global_load_lds_dwordx4 v226, s[20:21]
	s_mov_b32 m0, s34
	s_nop 0
	s_mov_b32 s34, m0
	s_mov_b32 m0, s16
	s_nop 0
	global_load_lds_dwordx4 v228, s[20:21]
	s_mov_b32 m0, s34
	s_mov_b32 s20, m0
	s_mov_b32 m0, s51
	s_nop 0
	global_load_lds_dwordx4 v225, s[8:9]
	s_mov_b32 m0, s20
	s_nop 0
	s_mov_b32 s20, m0
	s_mov_b32 m0, s17
	s_nop 0
	global_load_lds_dwordx4 v227, s[8:9]
	s_mov_b32 m0, s20
	s_waitcnt vmcnt(9)
	s_waitcnt lgkmcnt(0)
	s_barrier
	s_setprio 1
	s_waitcnt lgkmcnt(7)
	v_mfma_f32_16x16x32_bf16 v[82:85], v[166:169], v[182:185], v[82:85]
	v_mfma_f32_16x16x32_bf16 v[78:81], v[174:177], v[182:185], v[78:81]
	s_waitcnt lgkmcnt(5)
	v_mfma_f32_16x16x32_bf16 v[66:69], v[166:169], v[190:193], v[66:69]
	v_mfma_f32_16x16x32_bf16 v[62:65], v[174:177], v[190:193], v[62:65]
	s_waitcnt lgkmcnt(3)
	v_mfma_f32_16x16x32_bf16 v[50:53], v[166:169], v[198:201], v[50:53]
	v_mfma_f32_16x16x32_bf16 v[46:49], v[174:177], v[198:201], v[46:49]
	s_waitcnt lgkmcnt(1)
	v_mfma_f32_16x16x32_bf16 v[34:37], v[166:169], v[206:209], v[34:37]
	v_mfma_f32_16x16x32_bf16 v[30:33], v[174:177], v[206:209], v[30:33]
	v_mfma_f32_16x16x32_bf16 v[82:85], v[170:173], v[186:189], v[82:85]
	v_mfma_f32_16x16x32_bf16 v[78:81], v[178:181], v[186:189], v[78:81]
	v_mfma_f32_16x16x32_bf16 v[66:69], v[170:173], v[194:197], v[66:69]
	v_mfma_f32_16x16x32_bf16 v[62:65], v[178:181], v[194:197], v[62:65]
	v_mfma_f32_16x16x32_bf16 v[50:53], v[170:173], v[202:205], v[50:53]
	v_mfma_f32_16x16x32_bf16 v[46:49], v[178:181], v[202:205], v[46:49]
	s_waitcnt lgkmcnt(0)
	v_mfma_f32_16x16x32_bf16 v[34:37], v[170:173], v[210:213], v[34:37]
	v_mfma_f32_16x16x32_bf16 v[30:33], v[178:181], v[210:213], v[30:33]
	s_setprio 0
	s_setprio 1
	v_mfma_f32_16x16x32_bf16 v[74:77], v[150:153], v[182:185], v[74:77]
	v_mfma_f32_16x16x32_bf16 v[70:73], v[158:161], v[182:185], v[70:73]
	v_mfma_f32_16x16x32_bf16 v[58:61], v[150:153], v[190:193], v[58:61]
	v_mfma_f32_16x16x32_bf16 v[54:57], v[158:161], v[190:193], v[54:57]
	v_mfma_f32_16x16x32_bf16 v[42:45], v[150:153], v[198:201], v[42:45]
	v_mfma_f32_16x16x32_bf16 v[38:41], v[158:161], v[198:201], v[38:41]
	v_mfma_f32_16x16x32_bf16 v[26:29], v[150:153], v[206:209], v[26:29]
	v_mfma_f32_16x16x32_bf16 v[22:25], v[158:161], v[206:209], v[22:25]
	v_mfma_f32_16x16x32_bf16 v[74:77], v[154:157], v[186:189], v[74:77]
	v_mfma_f32_16x16x32_bf16 v[70:73], v[162:165], v[186:189], v[70:73]
	v_mfma_f32_16x16x32_bf16 v[58:61], v[154:157], v[194:197], v[58:61]
	v_mfma_f32_16x16x32_bf16 v[54:57], v[162:165], v[194:197], v[54:57]
	v_mfma_f32_16x16x32_bf16 v[42:45], v[154:157], v[202:205], v[42:45]
	v_mfma_f32_16x16x32_bf16 v[38:41], v[162:165], v[202:205], v[38:41]
	v_mfma_f32_16x16x32_bf16 v[26:29], v[154:157], v[210:213], v[26:29]
	v_mfma_f32_16x16x32_bf16 v[22:25], v[162:165], v[210:213], v[22:25]
	s_setprio 0
	s_barrier
	v_add_u32_e32 v4, 0x18000, v234
	ds_read_b128 v[166:169], v4
	ds_read_b128 v[170:173], v4 offset:1024
	ds_read_b128 v[174:177], v4 offset:2048
	ds_read_b128 v[178:181], v4 offset:3072
	v_add_u32_e32 v4, 0x1c000, v234
	ds_read_b128 v[150:153], v4
	ds_read_b128 v[154:157], v4 offset:1024
	ds_read_b128 v[158:161], v4 offset:2048
	ds_read_b128 v[162:165], v4 offset:3072
	ds_read_b128 v[206:209], v235 offset:32768
	ds_read_b128 v[210:213], v235 offset:33792
	ds_read_b128 v[198:201], v235 offset:34816
	ds_read_b128 v[202:205], v235 offset:35840
	ds_read_b128 v[190:193], v235 offset:36864
	ds_read_b128 v[194:197], v235 offset:37888
	ds_read_b128 v[182:185], v235 offset:38912
	ds_read_b128 v[186:189], v235 offset:39936
	s_and_b64 vcc, exec, s[40:41]
	s_cbranch_vccnz .LBB0_591
	ds_read_b128 v[6:9], v2 offset:128
	ds_read_b128 v[10:13], v2 offset:192
; #define PG8_STAGE(bufoff, gbase, voff) do { _Pragma("unroll") for (int _i = 0; _i < 2; ++_i) glds16_s((voff)[_i], (const void*)(gbase), ldsbase + (unsigned)((bufoff) + _i * 8192) + ldsw); } while (0)
; #define PG8_LDA(dst, b, h) do { _Pragma("unroll") for (int m = 0; m < 4; ++m) _Pragma("unroll") for (int k = 0; k < 2; ++k) dst[m][k] = *(const PG8_LAS bf16x8*)(lds + PG8_SA(b, h) + aoff + m * 2048 + k * 1024); } while (0)
; #define PG8_LDB(dst, b, h) do { _Pragma("unroll") for (int n = 0; n < 2; ++n) _Pragma("unroll") for (int k = 0; k < 2; ++k) dst[n][k] = *(const PG8_LAS bf16x8*)(lds + PG8_SB(b, h) + boff + n * 2048 + k * 1024); } while (0)
; #define PG8_LDX(pb, tp) do { _Pragma("unroll") for (int k = 0; k < 2; ++k) Ax[k] = *(const PG8_LAS bf16x8*)(lds + xoff + (pb) * 4096 + (tp) * 128 + k * 64); } while (0)
; #define PG8_MMA(ai, bj, At, Bt) do { __builtin_amdgcn_s_setprio(1); _Pragma("unroll") for (int m = 0; m < 4; ++m) _Pragma("unroll") for (int n = 0; n < 2; ++n) _Pragma("unroll") for (int k = 0; k < 2; ++k) \
;         acc[ai][bj][m][n] = __builtin_amdgcn_mfma_f32_16x16x32_bf16(Bt[n][k], At[m][k], acc[ai][bj][m][n], 0, 0, 0); __builtin_amdgcn_s_setprio(0); } while (0)
; #define PG8_WAIT_V(n) asm volatile("s_waitcnt vmcnt(" #n ")" ::: "memory")
; #define PG8_WAIT_L(n) asm volatile("s_waitcnt lgkmcnt(" #n ")" ::: "memory")
; #define PG8_BAR __builtin_amdgcn_s_barrier()
; #define PG8_SCHED __builtin_amdgcn_sched_barrier(0)
; template <class Epi, class Sched, bool HM = false>
; __device__ __forceinline__ void gemm_phase(PG8_LAS unsigned char* lds, const Gemm g, const Sched& S, const Epi& E) {
;     ...
;             PG8_LDB(B0, 1, 0); PG8_LDB(B1, 1, 1); PG8_SCHED; PG8_LDA(At, 1, 0); if (hasx) PG8_LDX(pb, 1); PG8_STAGE(PG8_SA(0, 1), a2 + hstepA, voffA);
;             PG8_WAIT_V(9); PG8_WAIT_L(0); PG8_BAR; PG8_MMA(0, 0, At, B0); PG8_MMA(0, 1, At, B1); if (hasx) PG8_MMAX(); PG8_BAR; PG8_SCHED;
.LBB0_591:
	s_add_u32 s8, s8, 0x80000
	s_addc_u32 s9, s9, 0
	s_mov_b32 s20, m0
	s_mov_b32 m0, s19
	s_nop 0
	global_load_lds_dwordx4 v225, s[8:9]
	s_mov_b32 m0, s20
	s_nop 0
	s_mov_b32 s20, m0
	s_mov_b32 m0, s28
	s_nop 0
	global_load_lds_dwordx4 v227, s[8:9]
	s_mov_b32 m0, s20
	s_waitcnt vmcnt(9)
	s_waitcnt lgkmcnt(0)
	s_barrier
	s_setprio 1
	s_waitcnt lgkmcnt(7)
	v_mfma_f32_16x16x32_bf16 v[146:149], v[166:169], v[206:209], v[146:149]
	v_mfma_f32_16x16x32_bf16 v[142:145], v[174:177], v[206:209], v[142:145]
	s_waitcnt lgkmcnt(5)
	v_mfma_f32_16x16x32_bf16 v[130:133], v[166:169], v[198:201], v[130:133]
	v_mfma_f32_16x16x32_bf16 v[126:129], v[174:177], v[198:201], v[126:129]
	s_waitcnt lgkmcnt(3)
	v_mfma_f32_16x16x32_bf16 v[114:117], v[166:169], v[190:193], v[114:117]
	v_mfma_f32_16x16x32_bf16 v[110:113], v[174:177], v[190:193], v[110:113]
	s_waitcnt lgkmcnt(1)
	v_mfma_f32_16x16x32_bf16 v[98:101], v[166:169], v[182:185], v[98:101]
	v_mfma_f32_16x16x32_bf16 v[94:97], v[174:177], v[182:185], v[94:97]
	v_mfma_f32_16x16x32_bf16 v[146:149], v[170:173], v[210:213], v[146:149]
	v_mfma_f32_16x16x32_bf16 v[142:145], v[178:181], v[210:213], v[142:145]
	v_mfma_f32_16x16x32_bf16 v[130:133], v[170:173], v[202:205], v[130:133]
	v_mfma_f32_16x16x32_bf16 v[126:129], v[178:181], v[202:205], v[126:129]
	v_mfma_f32_16x16x32_bf16 v[114:117], v[170:173], v[194:197], v[114:117]
	v_mfma_f32_16x16x32_bf16 v[110:113], v[178:181], v[194:197], v[110:113]
	s_waitcnt lgkmcnt(0)
	v_mfma_f32_16x16x32_bf16 v[98:101], v[170:173], v[186:189], v[98:101]
	v_mfma_f32_16x16x32_bf16 v[94:97], v[178:181], v[186:189], v[94:97]
	s_setprio 0
	s_setprio 1
	v_mfma_f32_16x16x32_bf16 v[138:141], v[150:153], v[206:209], v[138:141]
	v_mfma_f32_16x16x32_bf16 v[134:137], v[158:161], v[206:209], v[134:137]
	v_mfma_f32_16x16x32_bf16 v[122:125], v[150:153], v[198:201], v[122:125]
	v_mfma_f32_16x16x32_bf16 v[118:121], v[158:161], v[198:201], v[118:121]
	v_mfma_f32_16x16x32_bf16 v[106:109], v[150:153], v[190:193], v[106:109]
	v_mfma_f32_16x16x32_bf16 v[102:105], v[158:161], v[190:193], v[102:105]
	v_mfma_f32_16x16x32_bf16 v[90:93], v[150:153], v[182:185], v[90:93]
	v_mfma_f32_16x16x32_bf16 v[86:89], v[158:161], v[182:185], v[86:89]
	v_mfma_f32_16x16x32_bf16 v[138:141], v[154:157], v[210:213], v[138:141]
	v_mfma_f32_16x16x32_bf16 v[134:137], v[162:165], v[210:213], v[134:137]
	v_mfma_f32_16x16x32_bf16 v[122:125], v[154:157], v[202:205], v[122:125]
	v_mfma_f32_16x16x32_bf16 v[118:121], v[162:165], v[202:205], v[118:121]
	v_mfma_f32_16x16x32_bf16 v[106:109], v[154:157], v[194:197], v[106:109]
	v_mfma_f32_16x16x32_bf16 v[102:105], v[162:165], v[194:197], v[102:105]
	v_mfma_f32_16x16x32_bf16 v[90:93], v[154:157], v[186:189], v[90:93]
	v_mfma_f32_16x16x32_bf16 v[86:89], v[162:165], v[186:189], v[86:89]
	s_setprio 0
	s_and_b64 vcc, exec, s[40:41]
	s_cbranch_vccnz .LBB0_580
	s_and_b64 vcc, exec, s[42:43]
	s_mov_b64 s[8:9], -1
	s_cbranch_vccnz .LBB0_594
	v_mfma_f32_16x16x32_bf16 v[18:21], v[174:177], v[6:9], v[18:21]
	s_mov_b64 s[8:9], 0
	v_mfma_f32_16x16x32_bf16 v[14:17], v[158:161], v[6:9], v[14:17]
	v_mfma_f32_16x16x32_bf16 v[18:21], v[178:181], v[10:13], v[18:21]
	v_mfma_f32_16x16x32_bf16 v[14:17], v[162:165], v[10:13], v[14:17]

; #define PG8_STAGE(bufoff, gbase, voff) do { _Pragma("unroll") for (int _i = 0; _i < 2; ++_i) glds16_s((voff)[_i], (const void*)(gbase), ldsbase + (unsigned)((bufoff) + _i * 8192) + ldsw); } while (0)
; #define PG8_LDA(dst, b, h) do { _Pragma("unroll") for (int m = 0; m < 4; ++m) _Pragma("unroll") for (int k = 0; k < 2; ++k) dst[m][k] = *(const PG8_LAS bf16x8*)(lds + PG8_SA(b, h) + aoff + m * 2048 + k * 1024); } while (0)
; #define PG8_MMA(ai, bj, At, Bt) do { __builtin_amdgcn_s_setprio(1); _Pragma("unroll") for (int m = 0; m < 4; ++m) _Pragma("unroll") for (int n = 0; n < 2; ++n) _Pragma("unroll") for (int k = 0; k < 2; ++k) \
;         acc[ai][bj][m][n] = __builtin_amdgcn_mfma_f32_16x16x32_bf16(Bt[n][k], At[m][k], acc[ai][bj][m][n], 0, 0, 0); __builtin_amdgcn_s_setprio(0); } while (0)
; #define PG8_WAIT_V(n) asm volatile("s_waitcnt vmcnt(" #n ")" ::: "memory")
; #define PG8_WAIT_L(n) asm volatile("s_waitcnt lgkmcnt(" #n ")" ::: "memory")
; #define PG8_BAR __builtin_amdgcn_s_barrier()
; #define PG8_SCHED __builtin_amdgcn_sched_barrier(0)
; template <class Epi, class Sched, bool HM = false>
; __device__ __forceinline__ void gemm_phase(PG8_LAS unsigned char* lds, const Gemm g, const Sched& S, const Epi& E) {
;     ...
;             if (!HM) PG8_LDA(At, 1, 1); PG8_STAGE(PG8_SB(1, 0), b3, voffB); PG8_STAGE(PG8_SB(1, 1), b3 + hstepB, voffB); PG8_STAGE(PG8_SA(1, 0), a3, voffA);
;             PG8_WAIT_V(8); PG8_WAIT_L(0); PG8_BAR; if (!HM) { PG8_MMA(1, 0, At, B0); PG8_MMA(1, 1, At, B1); } PG8_BAR; PG8_SCHED;
;         }
.LBB0_985:
.LBB0_986:
	s_barrier
	ds_read_b128 v[182:185], v235 offset:49152
	ds_read_b128 v[186:189], v235 offset:50176
	ds_read_b128 v[190:193], v235 offset:51200
	ds_read_b128 v[194:197], v235 offset:52224
	ds_read_b128 v[198:201], v235 offset:53248
	ds_read_b128 v[202:205], v235 offset:54272
	ds_read_b128 v[206:209], v235 offset:55296
	ds_read_b128 v[210:213], v235 offset:56320
	s_mov_b32 s8, m0
	s_mov_b32 m0, s37
	s_nop 0
	global_load_lds_dwordx4 v226, s[6:7]
	s_mov_b32 m0, s8
	s_nop 0
	s_mov_b32 s8, m0
	s_mov_b32 m0, s51
	s_nop 0
	global_load_lds_dwordx4 v228, s[6:7]
	s_mov_b32 m0, s8
	s_add_u32 s6, s6, 0x80000
	s_addc_u32 s7, s7, 0
	s_mov_b32 s8, m0
	s_mov_b32 m0, s57
	s_nop 0
	global_load_lds_dwordx4 v226, s[6:7]
	s_mov_b32 m0, s8
	s_nop 0
	s_mov_b32 s8, m0
	s_mov_b32 m0, s58
	s_nop 0
	global_load_lds_dwordx4 v228, s[6:7]
	s_mov_b32 m0, s8
	s_mov_b32 s6, m0
	s_mov_b32 m0, s52
	s_nop 0
	global_load_lds_dwordx4 v225, s[4:5]
	s_mov_b32 m0, s6
	s_nop 0
	s_mov_b32 s6, m0
	s_mov_b32 m0, s56
	s_nop 0
	global_load_lds_dwordx4 v227, s[4:5]
	s_mov_b32 m0, s6
	s_waitcnt vmcnt(8)
	s_waitcnt lgkmcnt(0)
	s_barrier
	s_setprio 1
	s_waitcnt lgkmcnt(7)
	v_mfma_f32_16x16x32_bf16 v[82:85], v[166:169], v[182:185], v[82:85]
	v_mfma_f32_16x16x32_bf16 v[78:81], v[174:177], v[182:185], v[78:81]
	s_waitcnt lgkmcnt(5)
	v_mfma_f32_16x16x32_bf16 v[74:77], v[166:169], v[190:193], v[74:77]
	v_mfma_f32_16x16x32_bf16 v[66:69], v[174:177], v[190:193], v[66:69]
	s_waitcnt lgkmcnt(3)
	v_mfma_f32_16x16x32_bf16 v[58:61], v[166:169], v[198:201], v[58:61]
	v_mfma_f32_16x16x32_bf16 v[50:53], v[174:177], v[198:201], v[50:53]
	s_waitcnt lgkmcnt(1)
	v_mfma_f32_16x16x32_bf16 v[42:45], v[166:169], v[206:209], v[42:45]
	v_mfma_f32_16x16x32_bf16 v[34:37], v[174:177], v[206:209], v[34:37]
	v_mfma_f32_16x16x32_bf16 v[82:85], v[170:173], v[186:189], v[82:85]
	v_mfma_f32_16x16x32_bf16 v[78:81], v[178:181], v[186:189], v[78:81]
	v_mfma_f32_16x16x32_bf16 v[74:77], v[170:173], v[194:197], v[74:77]
	v_mfma_f32_16x16x32_bf16 v[66:69], v[178:181], v[194:197], v[66:69]
	v_mfma_f32_16x16x32_bf16 v[58:61], v[170:173], v[202:205], v[58:61]
	v_mfma_f32_16x16x32_bf16 v[50:53], v[178:181], v[202:205], v[50:53]
	s_waitcnt lgkmcnt(0)
	v_mfma_f32_16x16x32_bf16 v[42:45], v[170:173], v[210:213], v[42:45]
	v_mfma_f32_16x16x32_bf16 v[34:37], v[178:181], v[210:213], v[34:37]
	s_setprio 0
	s_setprio 1
	v_mfma_f32_16x16x32_bf16 v[70:73], v[150:153], v[182:185], v[70:73]
	v_mfma_f32_16x16x32_bf16 v[62:65], v[158:161], v[182:185], v[62:65]
	v_mfma_f32_16x16x32_bf16 v[54:57], v[150:153], v[190:193], v[54:57]
	v_mfma_f32_16x16x32_bf16 v[46:49], v[158:161], v[190:193], v[46:49]
	v_mfma_f32_16x16x32_bf16 v[38:41], v[150:153], v[198:201], v[38:41]
	v_mfma_f32_16x16x32_bf16 v[30:33], v[158:161], v[198:201], v[30:33]
	v_mfma_f32_16x16x32_bf16 v[26:29], v[150:153], v[206:209], v[26:29]
	v_mfma_f32_16x16x32_bf16 v[22:25], v[158:161], v[206:209], v[22:25]
	v_mfma_f32_16x16x32_bf16 v[70:73], v[154:157], v[186:189], v[70:73]
	v_mfma_f32_16x16x32_bf16 v[62:65], v[162:165], v[186:189], v[62:65]
	v_mfma_f32_16x16x32_bf16 v[54:57], v[154:157], v[194:197], v[54:57]
	v_mfma_f32_16x16x32_bf16 v[46:49], v[162:165], v[194:197], v[46:49]
	v_mfma_f32_16x16x32_bf16 v[38:41], v[154:157], v[202:205], v[38:41]
	v_mfma_f32_16x16x32_bf16 v[30:33], v[162:165], v[202:205], v[30:33]
	v_mfma_f32_16x16x32_bf16 v[26:29], v[154:157], v[210:213], v[26:29]
	v_mfma_f32_16x16x32_bf16 v[22:25], v[162:165], v[210:213], v[22:25]
	s_setprio 0
	s_barrier
	s_add_i32 s23, s23, 2
	s_addk_i32 s22, 0x1000
	s_add_u32 s89, s89, 0x100
	s_addc_u32 s90, s90, 0
	s_add_u32 s27, s27, 0x100
	s_addc_u32 s82, s82, 0
	s_cmp_gt_u32 s23, 29
	s_cbranch_scc1 .LBB0_1002

; #define PG8_STAGE(bufoff, gbase, voff) do { _Pragma("unroll") for (int _i = 0; _i < 2; ++_i) glds16_s((voff)[_i], (const void*)(gbase), ldsbase + (unsigned)((bufoff) + _i * 8192) + ldsw); } while (0)
; #define PG8_STAGEX(pb, gbase) glds16_s(voffX, (const void*)(gbase), ldsbase + (unsigned)(XOFF + (pb) * 4096) + ldsx)
; #define PG8_LDA(dst, b, h) do { _Pragma("unroll") for (int m = 0; m < 4; ++m) _Pragma("unroll") for (int k = 0; k < 2; ++k) dst[m][k] = *(const PG8_LAS bf16x8*)(lds + PG8_SA(b, h) + aoff + m * 2048 + k * 1024); } while (0)
; #define PG8_LDB(dst, b, h) do { _Pragma("unroll") for (int n = 0; n < 2; ++n) _Pragma("unroll") for (int k = 0; k < 2; ++k) dst[n][k] = *(const PG8_LAS bf16x8*)(lds + PG8_SB(b, h) + boff + n * 2048 + k * 1024); } while (0)
; #define PG8_LDX(pb, tp) do { _Pragma("unroll") for (int k = 0; k < 2; ++k) Ax[k] = *(const PG8_LAS bf16x8*)(lds + xoff + (pb) * 4096 + (tp) * 128 + k * 64); } while (0)
; #define PG8_MMA(ai, bj, At, Bt) do { __builtin_amdgcn_s_setprio(1); _Pragma("unroll") for (int m = 0; m < 4; ++m) _Pragma("unroll") for (int n = 0; n < 2; ++n) _Pragma("unroll") for (int k = 0; k < 2; ++k) \
;         acc[ai][bj][m][n] = __builtin_amdgcn_mfma_f32_16x16x32_bf16(Bt[n][k], At[m][k], acc[ai][bj][m][n], 0, 0, 0); __builtin_amdgcn_s_setprio(0); } while (0)
; #define PG8_WAIT_V(n) asm volatile("s_waitcnt vmcnt(" #n ")" ::: "memory")
; #define PG8_WAIT_L(n) asm volatile("s_waitcnt lgkmcnt(" #n ")" ::: "memory")
; #define PG8_BAR __builtin_amdgcn_s_barrier()
; #define PG8_SCHED __builtin_amdgcn_sched_barrier(0)
; template <class Epi, class Sched, bool HM = false>
; __device__ __forceinline__ void gemm_phase(PG8_LAS unsigned char* lds, const Gemm g, const Sched& S, const Epi& E) {
;     ...
;             PG8_LDB(B0, 0, 0); PG8_LDB(B1, 0, 1); PG8_SCHED; PG8_LDA(At, 0, 0); if (hasx) PG8_LDX(pb, 0); PG8_STAGE(PG8_SA(1, 1), a1 + hstepA, voffA); PG8_STAGEX(pb ^ 1, a2 + xstep);
;             PG8_WAIT_V(9); PG8_WAIT_L(0); PG8_BAR; PG8_MMA(0, 0, At, B0); PG8_MMA(0, 1, At, B1); if (hasx) PG8_MMAX(); PG8_BAR; PG8_SCHED;
.LBB0_989:
	s_add_u32 s42, s42, 0x80000
	s_addc_u32 s43, s43, 0
	s_mov_b32 s21, m0
	s_mov_b32 m0, s59
	s_nop 0
	global_load_lds_dwordx4 v225, s[42:43]
	s_mov_b32 m0, s21
	s_nop 0
	s_mov_b32 s21, m0
	s_mov_b32 m0, s83
	s_nop 0
	global_load_lds_dwordx4 v227, s[42:43]
	s_mov_b32 m0, s21
	s_add_u32 s42, s8, 0x100000
	s_addc_u32 s43, s9, 0
	s_xor_b32 s20, s20, 0x21400
	s_add_i32 s20, s30, s20
	s_mov_b32 s21, m0
	s_mov_b32 m0, s20
	s_nop 0
	global_load_lds_dwordx4 v229, s[42:43]
	s_mov_b32 m0, s21
	s_waitcnt vmcnt(9)
	s_waitcnt lgkmcnt(0)
	s_barrier
	s_setprio 1
	s_waitcnt lgkmcnt(7)
	v_mfma_f32_16x16x32_bf16 v[146:149], v[166:169], v[206:209], v[146:149]
	v_mfma_f32_16x16x32_bf16 v[142:145], v[174:177], v[206:209], v[142:145]
	s_waitcnt lgkmcnt(5)
	v_mfma_f32_16x16x32_bf16 v[138:141], v[166:169], v[198:201], v[138:141]
	v_mfma_f32_16x16x32_bf16 v[130:133], v[174:177], v[198:201], v[130:133]
	s_waitcnt lgkmcnt(3)
	v_mfma_f32_16x16x32_bf16 v[122:125], v[166:169], v[190:193], v[122:125]
	v_mfma_f32_16x16x32_bf16 v[114:117], v[174:177], v[190:193], v[114:117]
	s_waitcnt lgkmcnt(1)
	v_mfma_f32_16x16x32_bf16 v[106:109], v[166:169], v[182:185], v[106:109]
	v_mfma_f32_16x16x32_bf16 v[98:101], v[174:177], v[182:185], v[98:101]
	v_mfma_f32_16x16x32_bf16 v[146:149], v[170:173], v[210:213], v[146:149]
	v_mfma_f32_16x16x32_bf16 v[142:145], v[178:181], v[210:213], v[142:145]
	v_mfma_f32_16x16x32_bf16 v[138:141], v[170:173], v[202:205], v[138:141]
	v_mfma_f32_16x16x32_bf16 v[130:133], v[178:181], v[202:205], v[130:133]
	v_mfma_f32_16x16x32_bf16 v[122:125], v[170:173], v[194:197], v[122:125]
	v_mfma_f32_16x16x32_bf16 v[114:117], v[178:181], v[194:197], v[114:117]
	s_waitcnt lgkmcnt(0)
	v_mfma_f32_16x16x32_bf16 v[106:109], v[170:173], v[186:189], v[106:109]
	v_mfma_f32_16x16x32_bf16 v[98:101], v[178:181], v[186:189], v[98:101]
	s_setprio 0
	s_setprio 1
	v_mfma_f32_16x16x32_bf16 v[134:137], v[150:153], v[206:209], v[134:137]
	v_mfma_f32_16x16x32_bf16 v[126:129], v[158:161], v[206:209], v[126:129]
	v_mfma_f32_16x16x32_bf16 v[118:121], v[150:153], v[198:201], v[118:121]
	v_mfma_f32_16x16x32_bf16 v[110:113], v[158:161], v[198:201], v[110:113]
	v_mfma_f32_16x16x32_bf16 v[102:105], v[150:153], v[190:193], v[102:105]
	v_mfma_f32_16x16x32_bf16 v[94:97], v[158:161], v[190:193], v[94:97]
	v_mfma_f32_16x16x32_bf16 v[90:93], v[150:153], v[182:185], v[90:93]
	v_mfma_f32_16x16x32_bf16 v[86:89], v[158:161], v[182:185], v[86:89]
	v_mfma_f32_16x16x32_bf16 v[134:137], v[154:157], v[210:213], v[134:137]
	v_mfma_f32_16x16x32_bf16 v[126:129], v[162:165], v[210:213], v[126:129]
	v_mfma_f32_16x16x32_bf16 v[118:121], v[154:157], v[202:205], v[118:121]
	v_mfma_f32_16x16x32_bf16 v[110:113], v[162:165], v[202:205], v[110:113]
	v_mfma_f32_16x16x32_bf16 v[102:105], v[154:157], v[194:197], v[102:105]
	v_mfma_f32_16x16x32_bf16 v[94:97], v[162:165], v[194:197], v[94:97]
	v_mfma_f32_16x16x32_bf16 v[90:93], v[154:157], v[186:189], v[90:93]
	v_mfma_f32_16x16x32_bf16 v[86:89], v[162:165], v[186:189], v[86:89]
	s_setprio 0
	v_cndmask_b32_e64 v4, 0, 1, s[62:63]
	s_and_b64 vcc, exec, s[40:41]
	v_cmp_ne_u32_e64 s[42:43], 1, v4
	s_cbranch_vccnz .LBB0_995
	s_and_b64 vcc, exec, s[42:43]
	s_mov_b64 s[20:21], -1
	s_cbranch_vccnz .LBB0_992
	v_mfma_f32_16x16x32_bf16 v[18:21], v[174:177], v[6:9], v[18:21]
	s_mov_b64 s[20:21], 0
	v_mfma_f32_16x16x32_bf16 v[14:17], v[158:161], v[6:9], v[14:17]
	v_mfma_f32_16x16x32_bf16 v[18:21], v[178:181], v[10:13], v[18:21]
	v_mfma_f32_16x16x32_bf16 v[14:17], v[162:165], v[10:13], v[14:17]

; #define PG8_STAGE(bufoff, gbase, voff) do { _Pragma("unroll") for (int _i = 0; _i < 2; ++_i) glds16_s((voff)[_i], (const void*)(gbase), ldsbase + (unsigned)((bufoff) + _i * 8192) + ldsw); } while (0)
; #define PG8_LDA(dst, b, h) do { _Pragma("unroll") for (int m = 0; m < 4; ++m) _Pragma("unroll") for (int k = 0; k < 2; ++k) dst[m][k] = *(const PG8_LAS bf16x8*)(lds + PG8_SA(b, h) + aoff + m * 2048 + k * 1024); } while (0)
; #define PG8_LDB(dst, b, h) do { _Pragma("unroll") for (int n = 0; n < 2; ++n) _Pragma("unroll") for (int k = 0; k < 2; ++k) dst[n][k] = *(const PG8_LAS bf16x8*)(lds + PG8_SB(b, h) + boff + n * 2048 + k * 1024); } while (0)
; #define PG8_LDX(pb, tp) do { _Pragma("unroll") for (int k = 0; k < 2; ++k) Ax[k] = *(const PG8_LAS bf16x8*)(lds + xoff + (pb) * 4096 + (tp) * 128 + k * 64); } while (0)
; #define PG8_MMA(ai, bj, At, Bt) do { __builtin_amdgcn_s_setprio(1); _Pragma("unroll") for (int m = 0; m < 4; ++m) _Pragma("unroll") for (int n = 0; n < 2; ++n) _Pragma("unroll") for (int k = 0; k < 2; ++k) \
;         acc[ai][bj][m][n] = __builtin_amdgcn_mfma_f32_16x16x32_bf16(Bt[n][k], At[m][k], acc[ai][bj][m][n], 0, 0, 0); __builtin_amdgcn_s_setprio(0); } while (0)
; #define PG8_WAIT_V(n) asm volatile("s_waitcnt vmcnt(" #n ")" ::: "memory")
; #define PG8_WAIT_L(n) asm volatile("s_waitcnt lgkmcnt(" #n ")" ::: "memory")
; #define PG8_BAR __builtin_amdgcn_s_barrier()
; #define PG8_SCHED __builtin_amdgcn_sched_barrier(0)
; template <class Epi, class Sched, bool HM = false>
; __device__ __forceinline__ void gemm_phase(PG8_LAS unsigned char* lds, const Gemm g, const Sched& S, const Epi& E) {
;     ...
;             if (!HM) PG8_LDA(At, 0, 1); PG8_STAGE(PG8_SB(0, 0), b2, voffB); PG8_STAGE(PG8_SB(0, 1), b2 + hstepB, voffB); PG8_STAGE(PG8_SA(0, 0), a2, voffA);
;             PG8_WAIT_V(9); PG8_WAIT_L(0); PG8_BAR; if (!HM) { PG8_MMA(1, 0, At, B0); PG8_MMA(1, 1, At, B1); } PG8_BAR; PG8_SCHED;
;             PG8_LDB(B0, 1, 0); PG8_LDB(B1, 1, 1); PG8_SCHED; PG8_LDA(At, 1, 0); if (hasx) PG8_LDX(pb, 1); PG8_STAGE(PG8_SA(0, 1), a2 + hstepA, voffA);
.LBB0_994:
.LBB0_995:
	s_barrier
	ds_read_b128 v[182:185], v235 offset:16384
	ds_read_b128 v[186:189], v235 offset:17408
	ds_read_b128 v[190:193], v235 offset:18432
	ds_read_b128 v[194:197], v235 offset:19456
	ds_read_b128 v[198:201], v235 offset:20480
	ds_read_b128 v[202:205], v235 offset:21504
	ds_read_b128 v[206:209], v235 offset:22528
	ds_read_b128 v[210:213], v235 offset:23552
	s_mov_b32 s20, m0
	s_mov_b32 m0, s19
	s_nop 0
	global_load_lds_dwordx4 v226, s[34:35]
	s_mov_b32 m0, s20
	s_nop 0
	s_mov_b32 s20, m0
	s_mov_b32 m0, s24
	s_nop 0
	global_load_lds_dwordx4 v228, s[34:35]
	s_mov_b32 m0, s20
	s_add_u32 s20, s34, 0x80000
	s_addc_u32 s21, s35, 0
	s_mov_b32 s34, m0
	s_mov_b32 m0, s25
	s_nop 0
	global_load_lds_dwordx4 v226, s[20:21]
	s_mov_b32 m0, s34
	s_nop 0
	s_mov_b32 s34, m0
	s_mov_b32 m0, s28
	s_nop 0
	global_load_lds_dwordx4 v228, s[20:21]
	s_mov_b32 m0, s34
	s_mov_b32 s20, m0
	s_mov_b32 m0, s18
	s_nop 0
	global_load_lds_dwordx4 v225, s[8:9]
	s_mov_b32 m0, s20
	s_nop 0
	s_mov_b32 s20, m0
	s_mov_b32 m0, s29
	s_nop 0
	global_load_lds_dwordx4 v227, s[8:9]
	s_mov_b32 m0, s20
	s_waitcnt vmcnt(9)
	s_waitcnt lgkmcnt(0)
	s_barrier
	s_setprio 1
	s_waitcnt lgkmcnt(7)
	v_mfma_f32_16x16x32_bf16 v[82:85], v[166:169], v[182:185], v[82:85]
	v_mfma_f32_16x16x32_bf16 v[78:81], v[174:177], v[182:185], v[78:81]
	s_waitcnt lgkmcnt(5)
	v_mfma_f32_16x16x32_bf16 v[74:77], v[166:169], v[190:193], v[74:77]
	v_mfma_f32_16x16x32_bf16 v[66:69], v[174:177], v[190:193], v[66:69]
	s_waitcnt lgkmcnt(3)
	v_mfma_f32_16x16x32_bf16 v[58:61], v[166:169], v[198:201], v[58:61]
	v_mfma_f32_16x16x32_bf16 v[50:53], v[174:177], v[198:201], v[50:53]
	s_waitcnt lgkmcnt(1)
	v_mfma_f32_16x16x32_bf16 v[42:45], v[166:169], v[206:209], v[42:45]
	v_mfma_f32_16x16x32_bf16 v[34:37], v[174:177], v[206:209], v[34:37]
	v_mfma_f32_16x16x32_bf16 v[82:85], v[170:173], v[186:189], v[82:85]
	v_mfma_f32_16x16x32_bf16 v[78:81], v[178:181], v[186:189], v[78:81]
	v_mfma_f32_16x16x32_bf16 v[74:77], v[170:173], v[194:197], v[74:77]
	v_mfma_f32_16x16x32_bf16 v[66:69], v[178:181], v[194:197], v[66:69]
	v_mfma_f32_16x16x32_bf16 v[58:61], v[170:173], v[202:205], v[58:61]
	v_mfma_f32_16x16x32_bf16 v[50:53], v[178:181], v[202:205], v[50:53]
	s_waitcnt lgkmcnt(0)
	v_mfma_f32_16x16x32_bf16 v[42:45], v[170:173], v[210:213], v[42:45]
	v_mfma_f32_16x16x32_bf16 v[34:37], v[178:181], v[210:213], v[34:37]
	s_setprio 0
	s_setprio 1
	v_mfma_f32_16x16x32_bf16 v[70:73], v[150:153], v[182:185], v[70:73]
	v_mfma_f32_16x16x32_bf16 v[62:65], v[158:161], v[182:185], v[62:65]
	v_mfma_f32_16x16x32_bf16 v[54:57], v[150:153], v[190:193], v[54:57]
	v_mfma_f32_16x16x32_bf16 v[46:49], v[158:161], v[190:193], v[46:49]
	v_mfma_f32_16x16x32_bf16 v[38:41], v[150:153], v[198:201], v[38:41]
	v_mfma_f32_16x16x32_bf16 v[30:33], v[158:161], v[198:201], v[30:33]
	v_mfma_f32_16x16x32_bf16 v[26:29], v[150:153], v[206:209], v[26:29]
	v_mfma_f32_16x16x32_bf16 v[22:25], v[158:161], v[206:209], v[22:25]
	v_mfma_f32_16x16x32_bf16 v[70:73], v[154:157], v[186:189], v[70:73]
	v_mfma_f32_16x16x32_bf16 v[62:65], v[162:165], v[186:189], v[62:65]
	v_mfma_f32_16x16x32_bf16 v[54:57], v[154:157], v[194:197], v[54:57]
	v_mfma_f32_16x16x32_bf16 v[46:49], v[162:165], v[194:197], v[46:49]
	v_mfma_f32_16x16x32_bf16 v[38:41], v[154:157], v[202:205], v[38:41]
	v_mfma_f32_16x16x32_bf16 v[30:33], v[162:165], v[202:205], v[30:33]
	v_mfma_f32_16x16x32_bf16 v[26:29], v[154:157], v[210:213], v[26:29]
	v_mfma_f32_16x16x32_bf16 v[22:25], v[162:165], v[210:213], v[22:25]
	s_setprio 0
	s_barrier
	v_add_u32_e32 v4, 0x18000, v234
	ds_read_b128 v[166:169], v4
	ds_read_b128 v[170:173], v4 offset:1024
	ds_read_b128 v[174:177], v4 offset:2048
	ds_read_b128 v[178:181], v4 offset:3072
	v_add_u32_e32 v4, 0x1c000, v234
	ds_read_b128 v[150:153], v4
	ds_read_b128 v[154:157], v4 offset:1024
	ds_read_b128 v[158:161], v4 offset:2048
	ds_read_b128 v[162:165], v4 offset:3072
	ds_read_b128 v[206:209], v235 offset:32768
	ds_read_b128 v[210:213], v235 offset:33792
	ds_read_b128 v[198:201], v235 offset:34816
	ds_read_b128 v[202:205], v235 offset:35840
	ds_read_b128 v[190:193], v235 offset:36864
	ds_read_b128 v[194:197], v235 offset:37888
	ds_read_b128 v[182:185], v235 offset:38912
	ds_read_b128 v[186:189], v235 offset:39936
	s_and_b64 vcc, exec, s[40:41]
	s_cbranch_vccnz .LBB0_997
	ds_read_b128 v[6:9], v2 offset:128
	ds_read_b128 v[10:13], v2 offset:192
; #define PG8_STAGE(bufoff, gbase, voff) do { _Pragma("unroll") for (int _i = 0; _i < 2; ++_i) glds16_s((voff)[_i], (const void*)(gbase), ldsbase + (unsigned)((bufoff) + _i * 8192) + ldsw); } while (0)
; #define PG8_LDA(dst, b, h) do { _Pragma("unroll") for (int m = 0; m < 4; ++m) _Pragma("unroll") for (int k = 0; k < 2; ++k) dst[m][k] = *(const PG8_LAS bf16x8*)(lds + PG8_SA(b, h) + aoff + m * 2048 + k * 1024); } while (0)
; #define PG8_LDB(dst, b, h) do { _Pragma("unroll") for (int n = 0; n < 2; ++n) _Pragma("unroll") for (int k = 0; k < 2; ++k) dst[n][k] = *(const PG8_LAS bf16x8*)(lds + PG8_SB(b, h) + boff + n * 2048 + k * 1024); } while (0)
; #define PG8_LDX(pb, tp) do { _Pragma("unroll") for (int k = 0; k < 2; ++k) Ax[k] = *(const PG8_LAS bf16x8*)(lds + xoff + (pb) * 4096 + (tp) * 128 + k * 64); } while (0)
; #define PG8_MMA(ai, bj, At, Bt) do { __builtin_amdgcn_s_setprio(1); _Pragma("unroll") for (int m = 0; m < 4; ++m) _Pragma("unroll") for (int n = 0; n < 2; ++n) _Pragma("unroll") for (int k = 0; k < 2; ++k) \
;         acc[ai][bj][m][n] = __builtin_amdgcn_mfma_f32_16x16x32_bf16(Bt[n][k], At[m][k], acc[ai][bj][m][n], 0, 0, 0); __builtin_amdgcn_s_setprio(0); } while (0)
; #define PG8_WAIT_V(n) asm volatile("s_waitcnt vmcnt(" #n ")" ::: "memory")
; #define PG8_WAIT_L(n) asm volatile("s_waitcnt lgkmcnt(" #n ")" ::: "memory")
; #define PG8_BAR __builtin_amdgcn_s_barrier()
; #define PG8_SCHED __builtin_amdgcn_sched_barrier(0)
; template <class Epi, class Sched, bool HM = false>
; __device__ __forceinline__ void gemm_phase(PG8_LAS unsigned char* lds, const Gemm g, const Sched& S, const Epi& E) {
;     ...
;             PG8_LDB(B0, 1, 0); PG8_LDB(B1, 1, 1); PG8_SCHED; PG8_LDA(At, 1, 0); if (hasx) PG8_LDX(pb, 1); PG8_STAGE(PG8_SA(0, 1), a2 + hstepA, voffA);
;             PG8_WAIT_V(9); PG8_WAIT_L(0); PG8_BAR; PG8_MMA(0, 0, At, B0); PG8_MMA(0, 1, At, B1); if (hasx) PG8_MMAX(); PG8_BAR; PG8_SCHED;
.LBB0_997:
	s_add_u32 s8, s8, 0x80000
	s_addc_u32 s9, s9, 0
	s_mov_b32 s20, m0
	s_mov_b32 m0, s31
	s_nop 0
	global_load_lds_dwordx4 v225, s[8:9]
	s_mov_b32 m0, s20
	s_nop 0
	s_mov_b32 s20, m0
	s_mov_b32 m0, s36
	s_nop 0
	global_load_lds_dwordx4 v227, s[8:9]
	s_mov_b32 m0, s20
	s_waitcnt vmcnt(9)
	s_waitcnt lgkmcnt(0)
	s_barrier
	s_setprio 1
	s_waitcnt lgkmcnt(7)
	v_mfma_f32_16x16x32_bf16 v[146:149], v[166:169], v[206:209], v[146:149]
	v_mfma_f32_16x16x32_bf16 v[142:145], v[174:177], v[206:209], v[142:145]
	s_waitcnt lgkmcnt(5)
	v_mfma_f32_16x16x32_bf16 v[138:141], v[166:169], v[198:201], v[138:141]
	v_mfma_f32_16x16x32_bf16 v[130:133], v[174:177], v[198:201], v[130:133]
	s_waitcnt lgkmcnt(3)
	v_mfma_f32_16x16x32_bf16 v[122:125], v[166:169], v[190:193], v[122:125]
	v_mfma_f32_16x16x32_bf16 v[114:117], v[174:177], v[190:193], v[114:117]
	s_waitcnt lgkmcnt(1)
	v_mfma_f32_16x16x32_bf16 v[106:109], v[166:169], v[182:185], v[106:109]
	v_mfma_f32_16x16x32_bf16 v[98:101], v[174:177], v[182:185], v[98:101]
	v_mfma_f32_16x16x32_bf16 v[146:149], v[170:173], v[210:213], v[146:149]
	v_mfma_f32_16x16x32_bf16 v[142:145], v[178:181], v[210:213], v[142:145]
	v_mfma_f32_16x16x32_bf16 v[138:141], v[170:173], v[202:205], v[138:141]
	v_mfma_f32_16x16x32_bf16 v[130:133], v[178:181], v[202:205], v[130:133]
	v_mfma_f32_16x16x32_bf16 v[122:125], v[170:173], v[194:197], v[122:125]
	v_mfma_f32_16x16x32_bf16 v[114:117], v[178:181], v[194:197], v[114:117]
	s_waitcnt lgkmcnt(0)
	v_mfma_f32_16x16x32_bf16 v[106:109], v[170:173], v[186:189], v[106:109]
	v_mfma_f32_16x16x32_bf16 v[98:101], v[178:181], v[186:189], v[98:101]
	s_setprio 0
	s_setprio 1
	v_mfma_f32_16x16x32_bf16 v[134:137], v[150:153], v[206:209], v[134:137]
	v_mfma_f32_16x16x32_bf16 v[126:129], v[158:161], v[206:209], v[126:129]
	v_mfma_f32_16x16x32_bf16 v[118:121], v[150:153], v[198:201], v[118:121]
	v_mfma_f32_16x16x32_bf16 v[110:113], v[158:161], v[198:201], v[110:113]
	v_mfma_f32_16x16x32_bf16 v[102:105], v[150:153], v[190:193], v[102:105]
	v_mfma_f32_16x16x32_bf16 v[94:97], v[158:161], v[190:193], v[94:97]
	v_mfma_f32_16x16x32_bf16 v[90:93], v[150:153], v[182:185], v[90:93]
	v_mfma_f32_16x16x32_bf16 v[86:89], v[158:161], v[182:185], v[86:89]
	v_mfma_f32_16x16x32_bf16 v[134:137], v[154:157], v[210:213], v[134:137]
	v_mfma_f32_16x16x32_bf16 v[126:129], v[162:165], v[210:213], v[126:129]
	v_mfma_f32_16x16x32_bf16 v[118:121], v[154:157], v[202:205], v[118:121]
	v_mfma_f32_16x16x32_bf16 v[110:113], v[162:165], v[202:205], v[110:113]
	v_mfma_f32_16x16x32_bf16 v[102:105], v[154:157], v[194:197], v[102:105]
	v_mfma_f32_16x16x32_bf16 v[94:97], v[162:165], v[194:197], v[94:97]
	v_mfma_f32_16x16x32_bf16 v[90:93], v[154:157], v[186:189], v[90:93]
	v_mfma_f32_16x16x32_bf16 v[86:89], v[162:165], v[186:189], v[86:89]
	s_setprio 0
	s_and_b64 vcc, exec, s[40:41]
	s_cbranch_vccnz .LBB0_986
	s_and_b64 vcc, exec, s[42:43]
	s_mov_b64 s[8:9], -1
	s_cbranch_vccnz .LBB0_1000
	v_mfma_f32_16x16x32_bf16 v[18:21], v[174:177], v[6:9], v[18:21]
	s_mov_b64 s[8:9], 0
	v_mfma_f32_16x16x32_bf16 v[14:17], v[158:161], v[6:9], v[14:17]
	v_mfma_f32_16x16x32_bf16 v[18:21], v[178:181], v[10:13], v[18:21]
	v_mfma_f32_16x16x32_bf16 v[14:17], v[162:165], v[10:13], v[14:17]

; #define PG8_STAGE(bufoff, gbase, voff) do { _Pragma("unroll") for (int _i = 0; _i < 2; ++_i) glds16_s((voff)[_i], (const void*)(gbase), ldsbase + (unsigned)((bufoff) + _i * 8192) + ldsw); } while (0)
; #define PG8_LDA(dst, b, h) do { _Pragma("unroll") for (int m = 0; m < 4; ++m) _Pragma("unroll") for (int k = 0; k < 2; ++k) dst[m][k] = *(const PG8_LAS bf16x8*)(lds + PG8_SA(b, h) + aoff + m * 2048 + k * 1024); } while (0)
; #define PG8_MMA(ai, bj, At, Bt) do { __builtin_amdgcn_s_setprio(1); _Pragma("unroll") for (int m = 0; m < 4; ++m) _Pragma("unroll") for (int n = 0; n < 2; ++n) _Pragma("unroll") for (int k = 0; k < 2; ++k) \
;         acc[ai][bj][m][n] = __builtin_amdgcn_mfma_f32_16x16x32_bf16(Bt[n][k], At[m][k], acc[ai][bj][m][n], 0, 0, 0); __builtin_amdgcn_s_setprio(0); } while (0)
; #define PG8_WAIT_V(n) asm volatile("s_waitcnt vmcnt(" #n ")" ::: "memory")
; #define PG8_WAIT_L(n) asm volatile("s_waitcnt lgkmcnt(" #n ")" ::: "memory")
; #define PG8_BAR __builtin_amdgcn_s_barrier()
; #define PG8_SCHED __builtin_amdgcn_sched_barrier(0)
; template <class Epi, class Sched, bool HM = false>
; __device__ __forceinline__ void gemm_phase(PG8_LAS unsigned char* lds, const Gemm g, const Sched& S, const Epi& E) {
;     ...
;             if (!HM) PG8_LDA(At, 1, 1); PG8_STAGE(PG8_SB(1, 0), b3, voffB); PG8_STAGE(PG8_SB(1, 1), b3 + hstepB, voffB); PG8_STAGE(PG8_SA(1, 0), a3, voffA);
;             PG8_WAIT_V(8); PG8_WAIT_L(0); PG8_BAR; if (!HM) { PG8_MMA(1, 0, At, B0); PG8_MMA(1, 1, At, B1); } PG8_BAR; PG8_SCHED;
;         }
.LBB0_1267:
.LBB0_1268:
	s_barrier
	ds_read_b128 v[182:185], v235 offset:49152
	ds_read_b128 v[186:189], v235 offset:50176
	ds_read_b128 v[190:193], v235 offset:51200
	ds_read_b128 v[194:197], v235 offset:52224
	ds_read_b128 v[198:201], v235 offset:53248
	ds_read_b128 v[202:205], v235 offset:54272
	ds_read_b128 v[206:209], v235 offset:55296
	ds_read_b128 v[210:213], v235 offset:56320
	s_mov_b32 s8, m0
	s_mov_b32 m0, s51
	s_nop 0
	global_load_lds_dwordx4 v226, s[6:7]
	s_mov_b32 m0, s8
	s_nop 0
	s_mov_b32 s8, m0
	s_mov_b32 m0, s52
	s_nop 0
	global_load_lds_dwordx4 v228, s[6:7]
	s_mov_b32 m0, s8
	s_add_u32 s6, s6, 0x160000
	s_addc_u32 s7, s7, 0
	s_mov_b32 s8, m0
	s_mov_b32 m0, s74
	s_nop 0
	global_load_lds_dwordx4 v226, s[6:7]
	s_mov_b32 m0, s8
	s_nop 0
	s_mov_b32 s8, m0
	s_mov_b32 m0, s75
	s_nop 0
	global_load_lds_dwordx4 v228, s[6:7]
	s_mov_b32 m0, s8
	s_mov_b32 s6, m0
	s_mov_b32 m0, s62
	s_nop 0
	global_load_lds_dwordx4 v225, s[4:5]
	s_mov_b32 m0, s6
	s_nop 0
	s_mov_b32 s6, m0
	s_mov_b32 m0, s63
	s_nop 0
	global_load_lds_dwordx4 v227, s[4:5]
	s_mov_b32 m0, s6
	s_waitcnt vmcnt(8)
	s_waitcnt lgkmcnt(0)
	s_barrier
	s_setprio 1
	s_waitcnt lgkmcnt(7)
	v_mfma_f32_16x16x32_bf16 v[82:85], v[166:169], v[182:185], v[82:85]
	v_mfma_f32_16x16x32_bf16 v[78:81], v[174:177], v[182:185], v[78:81]
	s_waitcnt lgkmcnt(5)
	v_mfma_f32_16x16x32_bf16 v[74:77], v[166:169], v[190:193], v[74:77]
	v_mfma_f32_16x16x32_bf16 v[66:69], v[174:177], v[190:193], v[66:69]
	s_waitcnt lgkmcnt(3)
	v_mfma_f32_16x16x32_bf16 v[58:61], v[166:169], v[198:201], v[58:61]
	v_mfma_f32_16x16x32_bf16 v[50:53], v[174:177], v[198:201], v[50:53]
	s_waitcnt lgkmcnt(1)
	v_mfma_f32_16x16x32_bf16 v[42:45], v[166:169], v[206:209], v[42:45]
	v_mfma_f32_16x16x32_bf16 v[34:37], v[174:177], v[206:209], v[34:37]
	v_mfma_f32_16x16x32_bf16 v[82:85], v[170:173], v[186:189], v[82:85]
	v_mfma_f32_16x16x32_bf16 v[78:81], v[178:181], v[186:189], v[78:81]
	v_mfma_f32_16x16x32_bf16 v[74:77], v[170:173], v[194:197], v[74:77]
	v_mfma_f32_16x16x32_bf16 v[66:69], v[178:181], v[194:197], v[66:69]
	v_mfma_f32_16x16x32_bf16 v[58:61], v[170:173], v[202:205], v[58:61]
	v_mfma_f32_16x16x32_bf16 v[50:53], v[178:181], v[202:205], v[50:53]
	s_waitcnt lgkmcnt(0)
	v_mfma_f32_16x16x32_bf16 v[42:45], v[170:173], v[210:213], v[42:45]
	v_mfma_f32_16x16x32_bf16 v[34:37], v[178:181], v[210:213], v[34:37]
	s_setprio 0
	s_setprio 1
	v_mfma_f32_16x16x32_bf16 v[70:73], v[150:153], v[182:185], v[70:73]
	v_mfma_f32_16x16x32_bf16 v[62:65], v[158:161], v[182:185], v[62:65]
	v_mfma_f32_16x16x32_bf16 v[54:57], v[150:153], v[190:193], v[54:57]
	v_mfma_f32_16x16x32_bf16 v[46:49], v[158:161], v[190:193], v[46:49]
	v_mfma_f32_16x16x32_bf16 v[38:41], v[150:153], v[198:201], v[38:41]
	v_mfma_f32_16x16x32_bf16 v[30:33], v[158:161], v[198:201], v[30:33]
	v_mfma_f32_16x16x32_bf16 v[26:29], v[150:153], v[206:209], v[26:29]
	v_mfma_f32_16x16x32_bf16 v[22:25], v[158:161], v[206:209], v[22:25]
	v_mfma_f32_16x16x32_bf16 v[70:73], v[154:157], v[186:189], v[70:73]
	v_mfma_f32_16x16x32_bf16 v[62:65], v[162:165], v[186:189], v[62:65]
	v_mfma_f32_16x16x32_bf16 v[54:57], v[154:157], v[194:197], v[54:57]
	v_mfma_f32_16x16x32_bf16 v[46:49], v[162:165], v[194:197], v[46:49]
	v_mfma_f32_16x16x32_bf16 v[38:41], v[154:157], v[202:205], v[38:41]
	v_mfma_f32_16x16x32_bf16 v[30:33], v[162:165], v[202:205], v[30:33]
	v_mfma_f32_16x16x32_bf16 v[26:29], v[154:157], v[210:213], v[26:29]
	v_mfma_f32_16x16x32_bf16 v[22:25], v[162:165], v[210:213], v[22:25]
	s_setprio 0
	s_barrier
	s_add_i32 s23, s23, 2
	s_addk_i32 s22, 0x1000
	s_add_u32 s88, s88, 0x100
	s_addc_u32 s89, s89, 0
	s_add_u32 s27, s27, 0x100
	s_addc_u32 s82, s82, 0
	s_cmpk_gt_u32 s23, 0x55
	s_cbranch_scc1 .LBB0_1284

; #define PG8_STAGE(bufoff, gbase, voff) do { _Pragma("unroll") for (int _i = 0; _i < 2; ++_i) glds16_s((voff)[_i], (const void*)(gbase), ldsbase + (unsigned)((bufoff) + _i * 8192) + ldsw); } while (0)
; #define PG8_STAGEX(pb, gbase) glds16_s(voffX, (const void*)(gbase), ldsbase + (unsigned)(XOFF + (pb) * 4096) + ldsx)
; #define PG8_LDA(dst, b, h) do { _Pragma("unroll") for (int m = 0; m < 4; ++m) _Pragma("unroll") for (int k = 0; k < 2; ++k) dst[m][k] = *(const PG8_LAS bf16x8*)(lds + PG8_SA(b, h) + aoff + m * 2048 + k * 1024); } while (0)
; #define PG8_LDB(dst, b, h) do { _Pragma("unroll") for (int n = 0; n < 2; ++n) _Pragma("unroll") for (int k = 0; k < 2; ++k) dst[n][k] = *(const PG8_LAS bf16x8*)(lds + PG8_SB(b, h) + boff + n * 2048 + k * 1024); } while (0)
; #define PG8_LDX(pb, tp) do { _Pragma("unroll") for (int k = 0; k < 2; ++k) Ax[k] = *(const PG8_LAS bf16x8*)(lds + xoff + (pb) * 4096 + (tp) * 128 + k * 64); } while (0)
; #define PG8_MMA(ai, bj, At, Bt) do { __builtin_amdgcn_s_setprio(1); _Pragma("unroll") for (int m = 0; m < 4; ++m) _Pragma("unroll") for (int n = 0; n < 2; ++n) _Pragma("unroll") for (int k = 0; k < 2; ++k) \
;         acc[ai][bj][m][n] = __builtin_amdgcn_mfma_f32_16x16x32_bf16(Bt[n][k], At[m][k], acc[ai][bj][m][n], 0, 0, 0); __builtin_amdgcn_s_setprio(0); } while (0)
; #define PG8_WAIT_V(n) asm volatile("s_waitcnt vmcnt(" #n ")" ::: "memory")
; #define PG8_WAIT_L(n) asm volatile("s_waitcnt lgkmcnt(" #n ")" ::: "memory")
; #define PG8_BAR __builtin_amdgcn_s_barrier()
; #define PG8_SCHED __builtin_amdgcn_sched_barrier(0)
; template <class Epi, class Sched, bool HM = false>
; __device__ __forceinline__ void gemm_phase(PG8_LAS unsigned char* lds, const Gemm g, const Sched& S, const Epi& E) {
;     ...
;             PG8_LDB(B0, 0, 0); PG8_LDB(B1, 0, 1); PG8_SCHED; PG8_LDA(At, 0, 0); if (hasx) PG8_LDX(pb, 0); PG8_STAGE(PG8_SA(1, 1), a1 + hstepA, voffA); PG8_STAGEX(pb ^ 1, a2 + xstep);
;             PG8_WAIT_V(9); PG8_WAIT_L(0); PG8_BAR; PG8_MMA(0, 0, At, B0); PG8_MMA(0, 1, At, B1); if (hasx) PG8_MMAX(); PG8_BAR; PG8_SCHED;
.LBB0_1271:
	s_add_u32 s40, s40, 0x160000
	s_addc_u32 s41, s41, 0
	s_mov_b32 s21, m0
	s_mov_b32 m0, s76
	s_nop 0
	global_load_lds_dwordx4 v225, s[40:41]
	s_mov_b32 m0, s21
	s_nop 0
	s_mov_b32 s21, m0
	s_mov_b32 m0, s77
	s_nop 0
	global_load_lds_dwordx4 v227, s[40:41]
	s_mov_b32 m0, s21
	s_add_u32 s40, s8, 0x2c0000
	s_addc_u32 s41, s9, 0
	s_xor_b32 s20, s20, 0x21400
	s_add_i32 s20, s29, s20
	s_mov_b32 s21, m0
	s_mov_b32 m0, s20
	s_nop 0
	global_load_lds_dwordx4 v229, s[40:41]
	s_mov_b32 m0, s21
	s_waitcnt vmcnt(9)
	s_waitcnt lgkmcnt(0)
	s_barrier
	s_setprio 1
	s_waitcnt lgkmcnt(7)
	v_mfma_f32_16x16x32_bf16 v[146:149], v[166:169], v[206:209], v[146:149]
	v_mfma_f32_16x16x32_bf16 v[142:145], v[174:177], v[206:209], v[142:145]
	s_waitcnt lgkmcnt(5)
	v_mfma_f32_16x16x32_bf16 v[138:141], v[166:169], v[198:201], v[138:141]
	v_mfma_f32_16x16x32_bf16 v[130:133], v[174:177], v[198:201], v[130:133]
	s_waitcnt lgkmcnt(3)
	v_mfma_f32_16x16x32_bf16 v[122:125], v[166:169], v[190:193], v[122:125]
	v_mfma_f32_16x16x32_bf16 v[114:117], v[174:177], v[190:193], v[114:117]
	s_waitcnt lgkmcnt(1)
	v_mfma_f32_16x16x32_bf16 v[106:109], v[166:169], v[182:185], v[106:109]
	v_mfma_f32_16x16x32_bf16 v[98:101], v[174:177], v[182:185], v[98:101]
	v_mfma_f32_16x16x32_bf16 v[146:149], v[170:173], v[210:213], v[146:149]
	v_mfma_f32_16x16x32_bf16 v[142:145], v[178:181], v[210:213], v[142:145]
	v_mfma_f32_16x16x32_bf16 v[138:141], v[170:173], v[202:205], v[138:141]
	v_mfma_f32_16x16x32_bf16 v[130:133], v[178:181], v[202:205], v[130:133]
	v_mfma_f32_16x16x32_bf16 v[122:125], v[170:173], v[194:197], v[122:125]
	v_mfma_f32_16x16x32_bf16 v[114:117], v[178:181], v[194:197], v[114:117]
	s_waitcnt lgkmcnt(0)
	v_mfma_f32_16x16x32_bf16 v[106:109], v[170:173], v[186:189], v[106:109]
	v_mfma_f32_16x16x32_bf16 v[98:101], v[178:181], v[186:189], v[98:101]
	s_setprio 0
	s_setprio 1
	v_mfma_f32_16x16x32_bf16 v[134:137], v[150:153], v[206:209], v[134:137]
	v_mfma_f32_16x16x32_bf16 v[126:129], v[158:161], v[206:209], v[126:129]
	v_mfma_f32_16x16x32_bf16 v[118:121], v[150:153], v[198:201], v[118:121]
	v_mfma_f32_16x16x32_bf16 v[110:113], v[158:161], v[198:201], v[110:113]
	v_mfma_f32_16x16x32_bf16 v[102:105], v[150:153], v[190:193], v[102:105]
	v_mfma_f32_16x16x32_bf16 v[94:97], v[158:161], v[190:193], v[94:97]
	v_mfma_f32_16x16x32_bf16 v[90:93], v[150:153], v[182:185], v[90:93]
	v_mfma_f32_16x16x32_bf16 v[86:89], v[158:161], v[182:185], v[86:89]
	v_mfma_f32_16x16x32_bf16 v[134:137], v[154:157], v[210:213], v[134:137]
	v_mfma_f32_16x16x32_bf16 v[126:129], v[162:165], v[210:213], v[126:129]
	v_mfma_f32_16x16x32_bf16 v[118:121], v[154:157], v[202:205], v[118:121]
	v_mfma_f32_16x16x32_bf16 v[110:113], v[162:165], v[202:205], v[110:113]
	v_mfma_f32_16x16x32_bf16 v[102:105], v[154:157], v[194:197], v[102:105]
	v_mfma_f32_16x16x32_bf16 v[94:97], v[162:165], v[194:197], v[94:97]
	v_mfma_f32_16x16x32_bf16 v[90:93], v[154:157], v[186:189], v[90:93]
	v_mfma_f32_16x16x32_bf16 v[86:89], v[162:165], v[186:189], v[86:89]
	s_setprio 0
	v_cndmask_b32_e64 v4, 0, 1, s[46:47]
	s_and_b64 vcc, exec, s[38:39]
	v_cmp_ne_u32_e64 s[40:41], 1, v4
	s_cbranch_vccnz .LBB0_1277
	s_and_b64 vcc, exec, s[40:41]
	s_mov_b64 s[20:21], -1
	s_cbranch_vccnz .LBB0_1274
	v_mfma_f32_16x16x32_bf16 v[18:21], v[174:177], v[6:9], v[18:21]
	s_mov_b64 s[20:21], 0
	v_mfma_f32_16x16x32_bf16 v[14:17], v[158:161], v[6:9], v[14:17]
	v_mfma_f32_16x16x32_bf16 v[18:21], v[178:181], v[10:13], v[18:21]
	v_mfma_f32_16x16x32_bf16 v[14:17], v[162:165], v[10:13], v[14:17]

; #define PG8_STAGE(bufoff, gbase, voff) do { _Pragma("unroll") for (int _i = 0; _i < 2; ++_i) glds16_s((voff)[_i], (const void*)(gbase), ldsbase + (unsigned)((bufoff) + _i * 8192) + ldsw); } while (0)
; #define PG8_LDA(dst, b, h) do { _Pragma("unroll") for (int m = 0; m < 4; ++m) _Pragma("unroll") for (int k = 0; k < 2; ++k) dst[m][k] = *(const PG8_LAS bf16x8*)(lds + PG8_SA(b, h) + aoff + m * 2048 + k * 1024); } while (0)
; #define PG8_LDB(dst, b, h) do { _Pragma("unroll") for (int n = 0; n < 2; ++n) _Pragma("unroll") for (int k = 0; k < 2; ++k) dst[n][k] = *(const PG8_LAS bf16x8*)(lds + PG8_SB(b, h) + boff + n * 2048 + k * 1024); } while (0)
; #define PG8_LDX(pb, tp) do { _Pragma("unroll") for (int k = 0; k < 2; ++k) Ax[k] = *(const PG8_LAS bf16x8*)(lds + xoff + (pb) * 4096 + (tp) * 128 + k * 64); } while (0)
; #define PG8_MMA(ai, bj, At, Bt) do { __builtin_amdgcn_s_setprio(1); _Pragma("unroll") for (int m = 0; m < 4; ++m) _Pragma("unroll") for (int n = 0; n < 2; ++n) _Pragma("unroll") for (int k = 0; k < 2; ++k) \
;         acc[ai][bj][m][n] = __builtin_amdgcn_mfma_f32_16x16x32_bf16(Bt[n][k], At[m][k], acc[ai][bj][m][n], 0, 0, 0); __builtin_amdgcn_s_setprio(0); } while (0)
; #define PG8_WAIT_V(n) asm volatile("s_waitcnt vmcnt(" #n ")" ::: "memory")
; #define PG8_WAIT_L(n) asm volatile("s_waitcnt lgkmcnt(" #n ")" ::: "memory")
; #define PG8_BAR __builtin_amdgcn_s_barrier()
; #define PG8_SCHED __builtin_amdgcn_sched_barrier(0)
; template <class Epi, class Sched, bool HM = false>
; __device__ __forceinline__ void gemm_phase(PG8_LAS unsigned char* lds, const Gemm g, const Sched& S, const Epi& E) {
;     ...
;             if (!HM) PG8_LDA(At, 0, 1); PG8_STAGE(PG8_SB(0, 0), b2, voffB); PG8_STAGE(PG8_SB(0, 1), b2 + hstepB, voffB); PG8_STAGE(PG8_SA(0, 0), a2, voffA);
;             PG8_WAIT_V(9); PG8_WAIT_L(0); PG8_BAR; if (!HM) { PG8_MMA(1, 0, At, B0); PG8_MMA(1, 1, At, B1); } PG8_BAR; PG8_SCHED;
;             PG8_LDB(B0, 1, 0); PG8_LDB(B1, 1, 1); PG8_SCHED; PG8_LDA(At, 1, 0); if (hasx) PG8_LDX(pb, 1); PG8_STAGE(PG8_SA(0, 1), a2 + hstepA, voffA);
.LBB0_1276:
.LBB0_1277:
	s_barrier
	ds_read_b128 v[182:185], v235 offset:16384
	ds_read_b128 v[186:189], v235 offset:17408
	ds_read_b128 v[190:193], v235 offset:18432
	ds_read_b128 v[194:197], v235 offset:19456
	ds_read_b128 v[198:201], v235 offset:20480
	ds_read_b128 v[202:205], v235 offset:21504
	ds_read_b128 v[206:209], v235 offset:22528
	ds_read_b128 v[210:213], v235 offset:23552
	s_mov_b32 s20, m0
	s_mov_b32 m0, s18
	s_nop 0
	global_load_lds_dwordx4 v226, s[34:35]
	s_mov_b32 m0, s20
	s_nop 0
	s_mov_b32 s20, m0
	s_mov_b32 m0, s19
	s_nop 0
	global_load_lds_dwordx4 v228, s[34:35]
	s_mov_b32 m0, s20
	s_add_u32 s20, s34, 0x160000
	s_addc_u32 s21, s35, 0
	s_mov_b32 s34, m0
	s_mov_b32 m0, s24
	s_nop 0
	global_load_lds_dwordx4 v226, s[20:21]
	s_mov_b32 m0, s34
	s_nop 0
	s_mov_b32 s34, m0
	s_mov_b32 m0, s25
	s_nop 0
	global_load_lds_dwordx4 v228, s[20:21]
	s_mov_b32 m0, s34
	s_mov_b32 s20, m0
	s_mov_b32 m0, s17
	s_nop 0
	global_load_lds_dwordx4 v225, s[8:9]
	s_mov_b32 m0, s20
	s_nop 0
	s_mov_b32 s20, m0
	s_mov_b32 m0, s28
	s_nop 0
	global_load_lds_dwordx4 v227, s[8:9]
	s_mov_b32 m0, s20
	s_waitcnt vmcnt(9)
	s_waitcnt lgkmcnt(0)
	s_barrier
	s_setprio 1
	s_waitcnt lgkmcnt(7)
	v_mfma_f32_16x16x32_bf16 v[82:85], v[166:169], v[182:185], v[82:85]
	v_mfma_f32_16x16x32_bf16 v[78:81], v[174:177], v[182:185], v[78:81]
	s_waitcnt lgkmcnt(5)
	v_mfma_f32_16x16x32_bf16 v[74:77], v[166:169], v[190:193], v[74:77]
	v_mfma_f32_16x16x32_bf16 v[66:69], v[174:177], v[190:193], v[66:69]
	s_waitcnt lgkmcnt(3)
	v_mfma_f32_16x16x32_bf16 v[58:61], v[166:169], v[198:201], v[58:61]
	v_mfma_f32_16x16x32_bf16 v[50:53], v[174:177], v[198:201], v[50:53]
	s_waitcnt lgkmcnt(1)
	v_mfma_f32_16x16x32_bf16 v[42:45], v[166:169], v[206:209], v[42:45]
	v_mfma_f32_16x16x32_bf16 v[34:37], v[174:177], v[206:209], v[34:37]
	v_mfma_f32_16x16x32_bf16 v[82:85], v[170:173], v[186:189], v[82:85]
	v_mfma_f32_16x16x32_bf16 v[78:81], v[178:181], v[186:189], v[78:81]
	v_mfma_f32_16x16x32_bf16 v[74:77], v[170:173], v[194:197], v[74:77]
	v_mfma_f32_16x16x32_bf16 v[66:69], v[178:181], v[194:197], v[66:69]
	v_mfma_f32_16x16x32_bf16 v[58:61], v[170:173], v[202:205], v[58:61]
	v_mfma_f32_16x16x32_bf16 v[50:53], v[178:181], v[202:205], v[50:53]
	s_waitcnt lgkmcnt(0)
	v_mfma_f32_16x16x32_bf16 v[42:45], v[170:173], v[210:213], v[42:45]
	v_mfma_f32_16x16x32_bf16 v[34:37], v[178:181], v[210:213], v[34:37]
	s_setprio 0
	s_setprio 1
	v_mfma_f32_16x16x32_bf16 v[70:73], v[150:153], v[182:185], v[70:73]
	v_mfma_f32_16x16x32_bf16 v[62:65], v[158:161], v[182:185], v[62:65]
	v_mfma_f32_16x16x32_bf16 v[54:57], v[150:153], v[190:193], v[54:57]
	v_mfma_f32_16x16x32_bf16 v[46:49], v[158:161], v[190:193], v[46:49]
	v_mfma_f32_16x16x32_bf16 v[38:41], v[150:153], v[198:201], v[38:41]
	v_mfma_f32_16x16x32_bf16 v[30:33], v[158:161], v[198:201], v[30:33]
	v_mfma_f32_16x16x32_bf16 v[26:29], v[150:153], v[206:209], v[26:29]
	v_mfma_f32_16x16x32_bf16 v[22:25], v[158:161], v[206:209], v[22:25]
	v_mfma_f32_16x16x32_bf16 v[70:73], v[154:157], v[186:189], v[70:73]
	v_mfma_f32_16x16x32_bf16 v[62:65], v[162:165], v[186:189], v[62:65]
	v_mfma_f32_16x16x32_bf16 v[54:57], v[154:157], v[194:197], v[54:57]
	v_mfma_f32_16x16x32_bf16 v[46:49], v[162:165], v[194:197], v[46:49]
	v_mfma_f32_16x16x32_bf16 v[38:41], v[154:157], v[202:205], v[38:41]
	v_mfma_f32_16x16x32_bf16 v[30:33], v[162:165], v[202:205], v[30:33]
	v_mfma_f32_16x16x32_bf16 v[26:29], v[154:157], v[210:213], v[26:29]
	v_mfma_f32_16x16x32_bf16 v[22:25], v[162:165], v[210:213], v[22:25]
	s_setprio 0
	s_barrier
	v_add_u32_e32 v4, 0x18000, v234
	ds_read_b128 v[166:169], v4
	ds_read_b128 v[170:173], v4 offset:1024
	ds_read_b128 v[174:177], v4 offset:2048
	ds_read_b128 v[178:181], v4 offset:3072
	v_add_u32_e32 v4, 0x1c000, v234
	ds_read_b128 v[150:153], v4
	ds_read_b128 v[154:157], v4 offset:1024
	ds_read_b128 v[158:161], v4 offset:2048
	ds_read_b128 v[162:165], v4 offset:3072
	ds_read_b128 v[206:209], v235 offset:32768
	ds_read_b128 v[210:213], v235 offset:33792
	ds_read_b128 v[198:201], v235 offset:34816
	ds_read_b128 v[202:205], v235 offset:35840
	ds_read_b128 v[190:193], v235 offset:36864
	ds_read_b128 v[194:197], v235 offset:37888
	ds_read_b128 v[182:185], v235 offset:38912
	ds_read_b128 v[186:189], v235 offset:39936
	s_and_b64 vcc, exec, s[38:39]
	s_cbranch_vccnz .LBB0_1279
	ds_read_b128 v[6:9], v2 offset:128
	ds_read_b128 v[10:13], v2 offset:192
; #define PG8_STAGE(bufoff, gbase, voff) do { _Pragma("unroll") for (int _i = 0; _i < 2; ++_i) glds16_s((voff)[_i], (const void*)(gbase), ldsbase + (unsigned)((bufoff) + _i * 8192) + ldsw); } while (0)
; #define PG8_LDA(dst, b, h) do { _Pragma("unroll") for (int m = 0; m < 4; ++m) _Pragma("unroll") for (int k = 0; k < 2; ++k) dst[m][k] = *(const PG8_LAS bf16x8*)(lds + PG8_SA(b, h) + aoff + m * 2048 + k * 1024); } while (0)
; #define PG8_LDB(dst, b, h) do { _Pragma("unroll") for (int n = 0; n < 2; ++n) _Pragma("unroll") for (int k = 0; k < 2; ++k) dst[n][k] = *(const PG8_LAS bf16x8*)(lds + PG8_SB(b, h) + boff + n * 2048 + k * 1024); } while (0)
; #define PG8_LDX(pb, tp) do { _Pragma("unroll") for (int k = 0; k < 2; ++k) Ax[k] = *(const PG8_LAS bf16x8*)(lds + xoff + (pb) * 4096 + (tp) * 128 + k * 64); } while (0)
; #define PG8_MMA(ai, bj, At, Bt) do { __builtin_amdgcn_s_setprio(1); _Pragma("unroll") for (int m = 0; m < 4; ++m) _Pragma("unroll") for (int n = 0; n < 2; ++n) _Pragma("unroll") for (int k = 0; k < 2; ++k) \
;         acc[ai][bj][m][n] = __builtin_amdgcn_mfma_f32_16x16x32_bf16(Bt[n][k], At[m][k], acc[ai][bj][m][n], 0, 0, 0); __builtin_amdgcn_s_setprio(0); } while (0)
; #define PG8_WAIT_V(n) asm volatile("s_waitcnt vmcnt(" #n ")" ::: "memory")
; #define PG8_WAIT_L(n) asm volatile("s_waitcnt lgkmcnt(" #n ")" ::: "memory")
; #define PG8_BAR __builtin_amdgcn_s_barrier()
; #define PG8_SCHED __builtin_amdgcn_sched_barrier(0)
; template <class Epi, class Sched, bool HM = false>
; __device__ __forceinline__ void gemm_phase(PG8_LAS unsigned char* lds, const Gemm g, const Sched& S, const Epi& E) {
;     ...
;             PG8_LDB(B0, 1, 0); PG8_LDB(B1, 1, 1); PG8_SCHED; PG8_LDA(At, 1, 0); if (hasx) PG8_LDX(pb, 1); PG8_STAGE(PG8_SA(0, 1), a2 + hstepA, voffA);
;             PG8_WAIT_V(9); PG8_WAIT_L(0); PG8_BAR; PG8_MMA(0, 0, At, B0); PG8_MMA(0, 1, At, B1); if (hasx) PG8_MMAX(); PG8_BAR; PG8_SCHED;
.LBB0_1279:
	s_add_u32 s8, s8, 0x160000
	s_addc_u32 s9, s9, 0
	s_mov_b32 s20, m0
	s_mov_b32 m0, s30
	s_nop 0
	global_load_lds_dwordx4 v225, s[8:9]
	s_mov_b32 m0, s20
	s_nop 0
	s_mov_b32 s20, m0
	s_mov_b32 m0, s31
	s_nop 0
	global_load_lds_dwordx4 v227, s[8:9]
	s_mov_b32 m0, s20
	s_waitcnt vmcnt(9)
	s_waitcnt lgkmcnt(0)
	s_barrier
	s_setprio 1
	s_waitcnt lgkmcnt(7)
	v_mfma_f32_16x16x32_bf16 v[146:149], v[166:169], v[206:209], v[146:149]
	v_mfma_f32_16x16x32_bf16 v[142:145], v[174:177], v[206:209], v[142:145]
	s_waitcnt lgkmcnt(5)
	v_mfma_f32_16x16x32_bf16 v[138:141], v[166:169], v[198:201], v[138:141]
	v_mfma_f32_16x16x32_bf16 v[130:133], v[174:177], v[198:201], v[130:133]
	s_waitcnt lgkmcnt(3)
	v_mfma_f32_16x16x32_bf16 v[122:125], v[166:169], v[190:193], v[122:125]
	v_mfma_f32_16x16x32_bf16 v[114:117], v[174:177], v[190:193], v[114:117]
	s_waitcnt lgkmcnt(1)
	v_mfma_f32_16x16x32_bf16 v[106:109], v[166:169], v[182:185], v[106:109]
	v_mfma_f32_16x16x32_bf16 v[98:101], v[174:177], v[182:185], v[98:101]
	v_mfma_f32_16x16x32_bf16 v[146:149], v[170:173], v[210:213], v[146:149]
	v_mfma_f32_16x16x32_bf16 v[142:145], v[178:181], v[210:213], v[142:145]
	v_mfma_f32_16x16x32_bf16 v[138:141], v[170:173], v[202:205], v[138:141]
	v_mfma_f32_16x16x32_bf16 v[130:133], v[178:181], v[202:205], v[130:133]
	v_mfma_f32_16x16x32_bf16 v[122:125], v[170:173], v[194:197], v[122:125]
	v_mfma_f32_16x16x32_bf16 v[114:117], v[178:181], v[194:197], v[114:117]
	s_waitcnt lgkmcnt(0)
	v_mfma_f32_16x16x32_bf16 v[106:109], v[170:173], v[186:189], v[106:109]
	v_mfma_f32_16x16x32_bf16 v[98:101], v[178:181], v[186:189], v[98:101]
	s_setprio 0
	s_setprio 1
	v_mfma_f32_16x16x32_bf16 v[134:137], v[150:153], v[206:209], v[134:137]
	v_mfma_f32_16x16x32_bf16 v[126:129], v[158:161], v[206:209], v[126:129]
	v_mfma_f32_16x16x32_bf16 v[118:121], v[150:153], v[198:201], v[118:121]
	v_mfma_f32_16x16x32_bf16 v[110:113], v[158:161], v[198:201], v[110:113]
	v_mfma_f32_16x16x32_bf16 v[102:105], v[150:153], v[190:193], v[102:105]
	v_mfma_f32_16x16x32_bf16 v[94:97], v[158:161], v[190:193], v[94:97]
	v_mfma_f32_16x16x32_bf16 v[90:93], v[150:153], v[182:185], v[90:93]
	v_mfma_f32_16x16x32_bf16 v[86:89], v[158:161], v[182:185], v[86:89]
	v_mfma_f32_16x16x32_bf16 v[134:137], v[154:157], v[210:213], v[134:137]
	v_mfma_f32_16x16x32_bf16 v[126:129], v[162:165], v[210:213], v[126:129]
	v_mfma_f32_16x16x32_bf16 v[118:121], v[154:157], v[202:205], v[118:121]
	v_mfma_f32_16x16x32_bf16 v[110:113], v[162:165], v[202:205], v[110:113]
	v_mfma_f32_16x16x32_bf16 v[102:105], v[154:157], v[194:197], v[102:105]
	v_mfma_f32_16x16x32_bf16 v[94:97], v[162:165], v[194:197], v[94:97]
	v_mfma_f32_16x16x32_bf16 v[90:93], v[154:157], v[186:189], v[90:93]
	v_mfma_f32_16x16x32_bf16 v[86:89], v[162:165], v[186:189], v[86:89]
	s_setprio 0
	s_and_b64 vcc, exec, s[38:39]
	s_cbranch_vccnz .LBB0_1268
	s_and_b64 vcc, exec, s[40:41]
	s_mov_b64 s[8:9], -1
	s_cbranch_vccnz .LBB0_1282
	v_mfma_f32_16x16x32_bf16 v[18:21], v[174:177], v[6:9], v[18:21]
	s_mov_b64 s[8:9], 0
	v_mfma_f32_16x16x32_bf16 v[14:17], v[158:161], v[6:9], v[14:17]
	v_mfma_f32_16x16x32_bf16 v[18:21], v[178:181], v[10:13], v[18:21]
	v_mfma_f32_16x16x32_bf16 v[14:17], v[162:165], v[10:13], v[14:17]
